# GEMM K-loops: post-MFMA barrier moved one MFMA earlier (hand-off overlap of 16 cycles)
# speedup vs baseline: 1.0034x; 1.0034x over previous
; #define PG8_STAGE(bufoff, gbase, voff) do { _Pragma("unroll") for (int _i = 0; _i < 2; ++_i) \
;         __builtin_amdgcn_global_load_lds((const unsigned*)((const char*)(gbase) + (voff)[_i]), (PG8_LAS unsigned*)(lds + (bufoff) + ldsw + _i * 8192), 16, 0, 0); } while (0)
; #define PG8_LDA(dst, b, h) do { _Pragma("unroll") for (int m = 0; m < 4; ++m) _Pragma("unroll") for (int k = 0; k < 2; ++k) dst[m][k] = *(const PG8_LAS bf16x8*)(lds + PG8_SA(b, h) + aoff + m * 2048 + k * 1024); } while (0)
; #define PG8_LDB(dst, b, h) do { _Pragma("unroll") for (int n = 0; n < 2; ++n) _Pragma("unroll") for (int k = 0; k < 2; ++k) dst[n][k] = *(const PG8_LAS bf16x8*)(lds + PG8_SB(b, h) + boff + n * 2048 + k * 1024); } while (0)
; #define PG8_MMA(ai, bj, At, Bt) do { __builtin_amdgcn_s_setprio(1); _Pragma("unroll") for (int m = 0; m < 4; ++m) _Pragma("unroll") for (int n = 0; n < 2; ++n) _Pragma("unroll") for (int k = 0; k < 2; ++k) \
;         acc[ai][bj][m][n] = __builtin_amdgcn_mfma_f32_16x16x32_bf16(Bt[n][k], At[m][k], acc[ai][bj][m][n], 0, 0, 0); __builtin_amdgcn_s_setprio(0); } while (0)
; #define PG8_WAIT_V(n) asm volatile("s_waitcnt vmcnt(" #n ")" ::: "memory")
; #define PG8_WAIT_L(n) asm volatile("s_waitcnt lgkmcnt(" #n ")" ::: "memory")
; template <class Epi, class Sched, bool ALIGN_EPI = false, bool SP2 = false>
; __device__ __forceinline__ void gemm_phase(PG8_LAS unsigned char* lds, const Gemm g, const Sched& S, const Epi& E) {
;     ...
;             const bool last = (t == nt - 2);
;             const char* a1 = cA + (size_t)(t + 1) * kstep;
;             const char* a2 = last ? nA : cA + (size_t)(t + 2) * kstep; const char* b2 = last ? nB : cB + (size_t)(t + 2) * kstep;
;             const char* a3 = a2 + kstep; const char* b3 = b2 + kstep;
;             if (last && has_next) S.a_ready(nxt);
;             if constexpr (SP2) {
;             PG8_LDB(B0, 0, 0); PG8_LDB(B1, 0, 1); PG8_SCHED; PG8_LDA(At, 0, 0); PG8_STAGE(PG8_SA(1, 1), a1 + hstep, voffA);
;             PG8_WAIT_V(8); PG8_WAIT_L(0); PG8_BAR; PG8_MMA(0, 0, At, B0); PG8_MMA(0, 1, At, B1); PG8_BAR; PG8_SCHED;
;             PG8_LDA(At, 0, 1); PG8_STAGE(PG8_SB(0, 0), b2, voffB); PG8_STAGE(PG8_SB(0, 1), b2 + hstep, voffB); PG8_STAGE(PG8_SA(0, 0), a2, voffA);
;             PG8_WAIT_V(8); PG8_WAIT_L(0); PG8_BAR; PG8_MMA(1, 0, At, B0); PG8_MMA(1, 1, At, B1); PG8_BAR; PG8_SCHED;
.LBB0_119:
	ds_read_b128 v[154:157], v151
	ds_read_b128 v[158:161], v151 offset:1024
	ds_read_b128 v[162:165], v151 offset:2048
	ds_read_b128 v[166:169], v151 offset:3072
	ds_read_b128 v[170:173], v152
	ds_read_b128 v[174:177], v152 offset:1024
	ds_read_b128 v[178:181], v152 offset:2048
	ds_read_b128 v[182:185], v152 offset:3072
	s_add_u32 s70, s68, 0xfff80080
	s_addc_u32 s71, s69, -1
	s_cmp_eq_u32 s93, 28
	s_cselect_b32 s73, s35, s71
	s_cselect_b32 s72, s89, s70
	s_cselect_b32 s71, s21, s92
	s_cselect_b32 s70, s90, s91
	v_lshl_add_u64 v[218:219], s[68:69], 0, v[136:137]
	s_add_i32 m0, s19, 0xc000
	ds_read_b128 v[186:189], v153
	ds_read_b128 v[190:193], v153 offset:1024
	ds_read_b128 v[194:197], v153 offset:2048
	ds_read_b128 v[198:201], v153 offset:3072
	ds_read_b128 v[202:205], v153 offset:4096
	ds_read_b128 v[206:209], v153 offset:5120
	ds_read_b128 v[210:213], v153 offset:6144
	ds_read_b128 v[214:217], v153 offset:7168
	global_load_lds_dwordx4 v[218:219], off
	v_lshl_add_u64 v[218:219], s[68:69], 0, v[138:139]
	s_add_i32 m0, s19, 0xe000
	s_nop 0
	global_load_lds_dwordx4 v[218:219], off
	s_waitcnt vmcnt(8)
	s_waitcnt lgkmcnt(0)
	s_barrier
	s_setprio 1
	s_waitcnt lgkmcnt(0)
	v_mfma_f32_16x16x32_bf16 v[124:127], v[154:157], v[186:189], v[124:127]
	v_mfma_f32_16x16x32_bf16 v[120:123], v[162:165], v[186:189], v[120:123]
	v_mfma_f32_16x16x32_bf16 v[116:119], v[154:157], v[194:197], v[116:119]
	v_mfma_f32_16x16x32_bf16 v[112:115], v[162:165], v[194:197], v[112:115]
	v_mfma_f32_16x16x32_bf16 v[100:103], v[154:157], v[202:205], v[100:103]
	v_mfma_f32_16x16x32_bf16 v[96:99], v[162:165], v[202:205], v[96:99]
	v_mfma_f32_16x16x32_bf16 v[84:87], v[154:157], v[210:213], v[84:87]
	v_mfma_f32_16x16x32_bf16 v[80:83], v[162:165], v[210:213], v[80:83]
	v_mfma_f32_16x16x32_bf16 v[124:127], v[158:161], v[190:193], v[124:127]
	v_mfma_f32_16x16x32_bf16 v[120:123], v[166:169], v[190:193], v[120:123]
	v_mfma_f32_16x16x32_bf16 v[116:119], v[158:161], v[198:201], v[116:119]
	v_mfma_f32_16x16x32_bf16 v[112:115], v[166:169], v[198:201], v[112:115]
	v_mfma_f32_16x16x32_bf16 v[100:103], v[158:161], v[206:209], v[100:103]
	v_mfma_f32_16x16x32_bf16 v[96:99], v[166:169], v[206:209], v[96:99]
	v_mfma_f32_16x16x32_bf16 v[84:87], v[158:161], v[214:217], v[84:87]
	v_mfma_f32_16x16x32_bf16 v[80:83], v[166:169], v[214:217], v[80:83]
	s_setprio 0
	s_setprio 1
	v_mfma_f32_16x16x32_bf16 v[108:111], v[170:173], v[186:189], v[108:111]
	v_mfma_f32_16x16x32_bf16 v[104:107], v[178:181], v[186:189], v[104:107]
	v_mfma_f32_16x16x32_bf16 v[92:95], v[170:173], v[194:197], v[92:95]
	v_mfma_f32_16x16x32_bf16 v[88:91], v[178:181], v[194:197], v[88:91]
	v_mfma_f32_16x16x32_bf16 v[76:79], v[170:173], v[202:205], v[76:79]
	v_mfma_f32_16x16x32_bf16 v[72:75], v[178:181], v[202:205], v[72:75]
	v_mfma_f32_16x16x32_bf16 v[68:71], v[170:173], v[210:213], v[68:71]
	v_mfma_f32_16x16x32_bf16 v[64:67], v[178:181], v[210:213], v[64:67]
	v_mfma_f32_16x16x32_bf16 v[108:111], v[174:177], v[190:193], v[108:111]
	v_mfma_f32_16x16x32_bf16 v[104:107], v[182:185], v[190:193], v[104:107]
	v_mfma_f32_16x16x32_bf16 v[92:95], v[174:177], v[198:201], v[92:95]
	v_mfma_f32_16x16x32_bf16 v[88:91], v[182:185], v[198:201], v[88:91]
	v_mfma_f32_16x16x32_bf16 v[76:79], v[174:177], v[206:209], v[76:79]
	v_mfma_f32_16x16x32_bf16 v[72:75], v[182:185], v[206:209], v[72:75]
	v_mfma_f32_16x16x32_bf16 v[68:71], v[174:177], v[214:217], v[68:71]
	s_barrier
	v_mfma_f32_16x16x32_bf16 v[64:67], v[182:185], v[214:217], v[64:67]
	s_setprio 0
	s_add_i32 s94, s86, s55
	v_lshl_add_u64 v[218:219], s[70:71], 0, v[130:131]
	s_mov_b32 m0, s94
	ds_read_b128 v[186:189], v153 offset:16384
	ds_read_b128 v[190:193], v153 offset:17408
	ds_read_b128 v[194:197], v153 offset:18432
	ds_read_b128 v[198:201], v153 offset:19456
	ds_read_b128 v[202:205], v153 offset:20480
	ds_read_b128 v[206:209], v153 offset:21504
	ds_read_b128 v[210:213], v153 offset:22528
	ds_read_b128 v[214:217], v153 offset:23552
	global_load_lds_dwordx4 v[218:219], off
	s_add_i32 m0, s94, 0x2000
	s_add_u32 s94, s70, 0x80000
	v_lshl_add_u64 v[220:221], s[70:71], 0, v[134:135]
	s_addc_u32 s95, s71, 0
	s_add_i32 s96, s87, s55
	global_load_lds_dwordx4 v[220:221], off
	v_lshl_add_u64 v[222:223], s[94:95], 0, v[130:131]
	s_mov_b32 m0, s96
	v_lshl_add_u64 v[224:225], s[72:73], 0, v[132:133]
	global_load_lds_dwordx4 v[222:223], off
	v_lshl_add_u64 v[222:223], s[94:95], 0, v[134:135]
	s_add_i32 m0, s96, 0x2000
	s_nop 0
	global_load_lds_dwordx4 v[222:223], off
	v_lshl_add_u64 v[222:223], s[72:73], 0, v[128:129]
	s_mov_b32 m0, s19
	s_nop 0
	global_load_lds_dwordx4 v[222:223], off
	s_mov_b32 m0, s75
	s_nop 0
	global_load_lds_dwordx4 v[224:225], off
	s_waitcnt vmcnt(8)
	s_waitcnt lgkmcnt(0)
	s_barrier
; #define PG8_STAGE(bufoff, gbase, voff) do { _Pragma("unroll") for (int _i = 0; _i < 2; ++_i) \
;         __builtin_amdgcn_global_load_lds((const unsigned*)((const char*)(gbase) + (voff)[_i]), (PG8_LAS unsigned*)(lds + (bufoff) + ldsw + _i * 8192), 16, 0, 0); } while (0)
; #define PG8_LDA(dst, b, h) do { _Pragma("unroll") for (int m = 0; m < 4; ++m) _Pragma("unroll") for (int k = 0; k < 2; ++k) dst[m][k] = *(const PG8_LAS bf16x8*)(lds + PG8_SA(b, h) + aoff + m * 2048 + k * 1024); } while (0)
; #define PG8_LDB(dst, b, h) do { _Pragma("unroll") for (int n = 0; n < 2; ++n) _Pragma("unroll") for (int k = 0; k < 2; ++k) dst[n][k] = *(const PG8_LAS bf16x8*)(lds + PG8_SB(b, h) + boff + n * 2048 + k * 1024); } while (0)
; #define PG8_MMA(ai, bj, At, Bt) do { __builtin_amdgcn_s_setprio(1); _Pragma("unroll") for (int m = 0; m < 4; ++m) _Pragma("unroll") for (int n = 0; n < 2; ++n) _Pragma("unroll") for (int k = 0; k < 2; ++k) \
;         acc[ai][bj][m][n] = __builtin_amdgcn_mfma_f32_16x16x32_bf16(Bt[n][k], At[m][k], acc[ai][bj][m][n], 0, 0, 0); __builtin_amdgcn_s_setprio(0); } while (0)
; #define PG8_WAIT_V(n) asm volatile("s_waitcnt vmcnt(" #n ")" ::: "memory")
; #define PG8_WAIT_L(n) asm volatile("s_waitcnt lgkmcnt(" #n ")" ::: "memory")
; #define PG8_BAR __builtin_amdgcn_s_barrier()
; #define PG8_SCHED __builtin_amdgcn_sched_barrier(0)
; template <class Epi, class Sched, bool ALIGN_EPI = false, bool SP2 = false>
; __device__ __forceinline__ void gemm_phase(PG8_LAS unsigned char* lds, const Gemm g, const Sched& S, const Epi& E) {
;     ...
;             PG8_WAIT_V(8); PG8_WAIT_L(0); PG8_BAR; PG8_MMA(0, 0, At, B0); PG8_MMA(0, 1, At, B1); PG8_BAR; PG8_SCHED;
;             PG8_LDA(At, 0, 1); PG8_STAGE(PG8_SB(0, 0), b2, voffB); PG8_STAGE(PG8_SB(0, 1), b2 + hstep, voffB); PG8_STAGE(PG8_SA(0, 0), a2, voffA);
;             PG8_WAIT_V(8); PG8_WAIT_L(0); PG8_BAR; PG8_MMA(1, 0, At, B0); PG8_MMA(1, 1, At, B1); PG8_BAR; PG8_SCHED;
;             PG8_LDB(B0, 1, 0); PG8_LDB(B1, 1, 1); PG8_SCHED; PG8_LDA(At, 1, 0); PG8_STAGE(PG8_SA(0, 1), a2 + hstep, voffA);
;             PG8_WAIT_V(8); PG8_WAIT_L(0); PG8_BAR; PG8_MMA(0, 0, At, B0); PG8_MMA(0, 1, At, B1); PG8_BAR; PG8_SCHED;
	s_setprio 1
	s_waitcnt lgkmcnt(0)
	v_mfma_f32_16x16x32_bf16 v[60:63], v[154:157], v[186:189], v[60:63]
	v_mfma_f32_16x16x32_bf16 v[56:59], v[162:165], v[186:189], v[56:59]
	v_mfma_f32_16x16x32_bf16 v[52:55], v[154:157], v[194:197], v[52:55]
	v_mfma_f32_16x16x32_bf16 v[48:51], v[162:165], v[194:197], v[48:51]
	v_mfma_f32_16x16x32_bf16 v[36:39], v[154:157], v[202:205], v[36:39]
	v_mfma_f32_16x16x32_bf16 v[32:35], v[162:165], v[202:205], v[32:35]
	v_mfma_f32_16x16x32_bf16 v[20:23], v[154:157], v[210:213], v[20:23]
	v_mfma_f32_16x16x32_bf16 v[16:19], v[162:165], v[210:213], v[16:19]
	v_mfma_f32_16x16x32_bf16 v[60:63], v[158:161], v[190:193], v[60:63]
	v_mfma_f32_16x16x32_bf16 v[56:59], v[166:169], v[190:193], v[56:59]
	v_mfma_f32_16x16x32_bf16 v[52:55], v[158:161], v[198:201], v[52:55]
	v_mfma_f32_16x16x32_bf16 v[48:51], v[166:169], v[198:201], v[48:51]
	v_mfma_f32_16x16x32_bf16 v[36:39], v[158:161], v[206:209], v[36:39]
	v_mfma_f32_16x16x32_bf16 v[32:35], v[166:169], v[206:209], v[32:35]
	v_mfma_f32_16x16x32_bf16 v[20:23], v[158:161], v[214:217], v[20:23]
	v_mfma_f32_16x16x32_bf16 v[16:19], v[166:169], v[214:217], v[16:19]
	s_setprio 0
	s_setprio 1
	v_mfma_f32_16x16x32_bf16 v[44:47], v[170:173], v[186:189], v[44:47]
	v_mfma_f32_16x16x32_bf16 v[40:43], v[178:181], v[186:189], v[40:43]
	v_mfma_f32_16x16x32_bf16 v[28:31], v[170:173], v[194:197], v[28:31]
	v_mfma_f32_16x16x32_bf16 v[24:27], v[178:181], v[194:197], v[24:27]
	v_mfma_f32_16x16x32_bf16 v[12:15], v[170:173], v[202:205], v[12:15]
	v_mfma_f32_16x16x32_bf16 v[8:11], v[178:181], v[202:205], v[8:11]
	v_mfma_f32_16x16x32_bf16 v[4:7], v[170:173], v[210:213], v[4:7]
	v_mfma_f32_16x16x32_bf16 v[0:3], v[178:181], v[210:213], v[0:3]
	v_mfma_f32_16x16x32_bf16 v[44:47], v[174:177], v[190:193], v[44:47]
	v_mfma_f32_16x16x32_bf16 v[40:43], v[182:185], v[190:193], v[40:43]
	v_mfma_f32_16x16x32_bf16 v[28:31], v[174:177], v[198:201], v[28:31]
	v_mfma_f32_16x16x32_bf16 v[24:27], v[182:185], v[198:201], v[24:27]
	v_mfma_f32_16x16x32_bf16 v[12:15], v[174:177], v[206:209], v[12:15]
	v_mfma_f32_16x16x32_bf16 v[8:11], v[182:185], v[206:209], v[8:11]
	v_mfma_f32_16x16x32_bf16 v[4:7], v[174:177], v[214:217], v[4:7]
	s_barrier
	v_mfma_f32_16x16x32_bf16 v[0:3], v[182:185], v[214:217], v[0:3]
	s_setprio 0
	s_add_i32 s94, 0, 0x18000
	s_add_i32 s95, 0, 0x1c000
	v_add_u32_e32 v166, s94, v149
	v_add_u32_e32 v182, s95, v149
	ds_read_b128 v[154:157], v166
	ds_read_b128 v[158:161], v166 offset:1024
	ds_read_b128 v[162:165], v166 offset:2048
	ds_read_b128 v[166:169], v166 offset:3072
	ds_read_b128 v[170:173], v182
	ds_read_b128 v[174:177], v182 offset:1024
	ds_read_b128 v[178:181], v182 offset:2048
	ds_read_b128 v[182:185], v182 offset:3072
	s_add_u32 s72, s72, 0x80000
	s_addc_u32 s73, s73, 0
	s_mov_b32 m0, s76
	v_lshl_add_u64 v[226:227], s[72:73], 0, v[128:129]
	ds_read_b128 v[186:189], v153 offset:32768
	ds_read_b128 v[190:193], v153 offset:33792
	ds_read_b128 v[194:197], v153 offset:34816
	ds_read_b128 v[198:201], v153 offset:35840
	ds_read_b128 v[202:205], v153 offset:36864
	ds_read_b128 v[206:209], v153 offset:37888
	ds_read_b128 v[210:213], v153 offset:38912
	ds_read_b128 v[214:217], v153 offset:39936
	global_load_lds_dwordx4 v[226:227], off
	v_lshl_add_u64 v[226:227], s[72:73], 0, v[132:133]
	s_mov_b32 m0, s77
	s_nop 0
	global_load_lds_dwordx4 v[226:227], off
	s_waitcnt vmcnt(8)
	s_waitcnt lgkmcnt(0)
	s_barrier
	s_setprio 1
	s_waitcnt lgkmcnt(0)
	v_mfma_f32_16x16x32_bf16 v[124:127], v[154:157], v[186:189], v[124:127]
	v_mfma_f32_16x16x32_bf16 v[120:123], v[162:165], v[186:189], v[120:123]
	v_mfma_f32_16x16x32_bf16 v[116:119], v[154:157], v[194:197], v[116:119]
	v_mfma_f32_16x16x32_bf16 v[112:115], v[162:165], v[194:197], v[112:115]
	v_mfma_f32_16x16x32_bf16 v[100:103], v[154:157], v[202:205], v[100:103]
	v_mfma_f32_16x16x32_bf16 v[96:99], v[162:165], v[202:205], v[96:99]
	v_mfma_f32_16x16x32_bf16 v[84:87], v[154:157], v[210:213], v[84:87]
	v_mfma_f32_16x16x32_bf16 v[80:83], v[162:165], v[210:213], v[80:83]
	v_mfma_f32_16x16x32_bf16 v[124:127], v[158:161], v[190:193], v[124:127]
	v_mfma_f32_16x16x32_bf16 v[120:123], v[166:169], v[190:193], v[120:123]
	v_mfma_f32_16x16x32_bf16 v[116:119], v[158:161], v[198:201], v[116:119]
	v_mfma_f32_16x16x32_bf16 v[112:115], v[166:169], v[198:201], v[112:115]
	v_mfma_f32_16x16x32_bf16 v[100:103], v[158:161], v[206:209], v[100:103]
	v_mfma_f32_16x16x32_bf16 v[96:99], v[166:169], v[206:209], v[96:99]
	v_mfma_f32_16x16x32_bf16 v[84:87], v[158:161], v[214:217], v[84:87]
	v_mfma_f32_16x16x32_bf16 v[80:83], v[166:169], v[214:217], v[80:83]
	s_setprio 0
	s_setprio 1
	v_mfma_f32_16x16x32_bf16 v[108:111], v[170:173], v[186:189], v[108:111]
	v_mfma_f32_16x16x32_bf16 v[104:107], v[178:181], v[186:189], v[104:107]
	v_mfma_f32_16x16x32_bf16 v[92:95], v[170:173], v[194:197], v[92:95]
	v_mfma_f32_16x16x32_bf16 v[88:91], v[178:181], v[194:197], v[88:91]
	v_mfma_f32_16x16x32_bf16 v[76:79], v[170:173], v[202:205], v[76:79]
	v_mfma_f32_16x16x32_bf16 v[72:75], v[178:181], v[202:205], v[72:75]
	v_mfma_f32_16x16x32_bf16 v[68:71], v[170:173], v[210:213], v[68:71]
	v_mfma_f32_16x16x32_bf16 v[64:67], v[178:181], v[210:213], v[64:67]
	v_mfma_f32_16x16x32_bf16 v[108:111], v[174:177], v[190:193], v[108:111]
	v_mfma_f32_16x16x32_bf16 v[104:107], v[182:185], v[190:193], v[104:107]
	v_mfma_f32_16x16x32_bf16 v[92:95], v[174:177], v[198:201], v[92:95]
	v_mfma_f32_16x16x32_bf16 v[88:91], v[182:185], v[198:201], v[88:91]
	v_mfma_f32_16x16x32_bf16 v[76:79], v[174:177], v[206:209], v[76:79]
	v_mfma_f32_16x16x32_bf16 v[72:75], v[182:185], v[206:209], v[72:75]
	v_mfma_f32_16x16x32_bf16 v[68:71], v[174:177], v[214:217], v[68:71]
	s_barrier
; #define PG8_STAGE(bufoff, gbase, voff) do { _Pragma("unroll") for (int _i = 0; _i < 2; ++_i) \
;         __builtin_amdgcn_global_load_lds((const unsigned*)((const char*)(gbase) + (voff)[_i]), (PG8_LAS unsigned*)(lds + (bufoff) + ldsw + _i * 8192), 16, 0, 0); } while (0)
; #define PG8_WAIT_V(n) asm volatile("s_waitcnt vmcnt(" #n ")" ::: "memory")
; #define PG8_WAIT_L(n) asm volatile("s_waitcnt lgkmcnt(" #n ")" ::: "memory")
; template <class Epi, class Sched, bool ALIGN_EPI = false, bool SP2 = false>
; __device__ __forceinline__ void gemm_phase(PG8_LAS unsigned char* lds, const Gemm g, const Sched& S, const Epi& E) {
;     ...
;             PG8_WAIT_V(8); PG8_WAIT_L(0); PG8_BAR; PG8_MMA(0, 0, At, B0); PG8_MMA(0, 1, At, B1); PG8_BAR; PG8_SCHED;
;             PG8_LDA(At, 1, 1); PG8_STAGE(PG8_SB(1, 0), b3, voffB); PG8_STAGE(PG8_SB(1, 1), b3 + hstep, voffB); PG8_STAGE(PG8_SA(1, 0), a3, voffA);
;             PG8_WAIT_V(8); PG8_WAIT_L(0); PG8_BAR; PG8_MMA(1, 0, At, B0); PG8_MMA(1, 1, At, B1); PG8_BAR; PG8_SCHED;
;             } else {
;             PG8_LDB(B0, 0, 0); PG8_SCHED; PG8_LDA(At, 0, 0); PG8_STAGE(PG8_SA(1, 1), a1 + hstep, voffA);
;             PG8_WAIT_L(8); PG8_BAR; PG8_WAIT_L(0); PG8_MMA(0, 0, At, B0); PG8_BAR; PG8_SCHED;
;             PG8_LDB(B1, 0, 1); PG8_STAGE(PG8_SB(0, 0), b2, voffB);
;             PG8_BAR; PG8_WAIT_L(0); PG8_MMA(0, 1, At, B1); PG8_BAR;
;             PG8_LDA(At, 0, 1); PG8_STAGE(PG8_SA(0, 0), a2, voffA);
;             PG8_BAR; PG8_WAIT_L(0); PG8_MMA(1, 0, At, B0); PG8_BAR; PG8_SCHED;
;             PG8_STAGE(PG8_SB(0, 1), b2 + hstep, voffB);
;             PG8_WAIT_V(6); PG8_BAR; PG8_MMA(1, 1, At, B1); PG8_BAR;
;             PG8_LDB(B0, 1, 0); PG8_SCHED; PG8_LDA(At, 1, 0); PG8_STAGE(PG8_SA(0, 1), a2 + hstep, voffA);
;             PG8_WAIT_L(8); PG8_BAR; PG8_WAIT_L(0); PG8_MMA(0, 0, At, B0); PG8_BAR; PG8_SCHED;
;             PG8_LDB(B1, 1, 1); PG8_STAGE(PG8_SB(1, 0), b3, voffB);
;             PG8_BAR; PG8_WAIT_L(0); PG8_MMA(0, 1, At, B1); PG8_BAR;
;             PG8_LDA(At, 1, 1); PG8_STAGE(PG8_SA(1, 0), a3, voffA);
;             PG8_BAR; PG8_WAIT_L(0); PG8_MMA(1, 0, At, B0); PG8_BAR; PG8_SCHED;
;             PG8_STAGE(PG8_SB(1, 1), b3 + hstep, voffB);
;             PG8_WAIT_V(6); PG8_BAR; PG8_MMA(1, 1, At, B1); PG8_BAR;
;             }
;         }
;         if constexpr (ALIGN_EPI) { if (wr == 0) PG8_BAR; }
	v_mfma_f32_16x16x32_bf16 v[64:67], v[182:185], v[214:217], v[64:67]
	s_setprio 0
	s_add_i32 s72, s94, s55
	v_lshl_add_u64 v[218:219], v[218:219], 0, s[10:11]
	s_mov_b32 m0, s72
	ds_read_b128 v[186:189], v153 offset:49152
	ds_read_b128 v[190:193], v153 offset:50176
	ds_read_b128 v[194:197], v153 offset:51200
	ds_read_b128 v[198:201], v153 offset:52224
	ds_read_b128 v[202:205], v153 offset:53248
	ds_read_b128 v[206:209], v153 offset:54272
	ds_read_b128 v[210:213], v153 offset:55296
	ds_read_b128 v[214:217], v153 offset:56320
	global_load_lds_dwordx4 v[218:219], off
	s_add_i32 m0, s72, 0x2000
	s_add_u32 s70, s70, 0x80080
	v_lshl_add_u64 v[218:219], v[220:221], 0, s[10:11]
	s_addc_u32 s71, s71, 0
	s_add_i32 s72, s95, s55
	global_load_lds_dwordx4 v[218:219], off
	v_lshl_add_u64 v[218:219], s[70:71], 0, v[130:131]
	s_mov_b32 m0, s72
	s_nop 0
	global_load_lds_dwordx4 v[218:219], off
	v_lshl_add_u64 v[218:219], s[70:71], 0, v[134:135]
	s_add_i32 m0, s72, 0x2000
	s_nop 0
	global_load_lds_dwordx4 v[218:219], off
	v_lshl_add_u64 v[218:219], v[222:223], 0, s[10:11]
	s_mov_b32 m0, s79
	s_nop 0
	global_load_lds_dwordx4 v[218:219], off
	v_lshl_add_u64 v[218:219], v[224:225], 0, s[10:11]
	s_mov_b32 m0, s80
	s_nop 0
	global_load_lds_dwordx4 v[218:219], off
	s_waitcnt vmcnt(8)
	s_waitcnt lgkmcnt(0)
	s_barrier
	s_setprio 1
	s_waitcnt lgkmcnt(0)
	v_mfma_f32_16x16x32_bf16 v[60:63], v[154:157], v[186:189], v[60:63]
	v_mfma_f32_16x16x32_bf16 v[56:59], v[162:165], v[186:189], v[56:59]
	v_mfma_f32_16x16x32_bf16 v[52:55], v[154:157], v[194:197], v[52:55]
	v_mfma_f32_16x16x32_bf16 v[48:51], v[162:165], v[194:197], v[48:51]
	v_mfma_f32_16x16x32_bf16 v[36:39], v[154:157], v[202:205], v[36:39]
	v_mfma_f32_16x16x32_bf16 v[32:35], v[162:165], v[202:205], v[32:35]
	v_mfma_f32_16x16x32_bf16 v[20:23], v[154:157], v[210:213], v[20:23]
	v_mfma_f32_16x16x32_bf16 v[16:19], v[162:165], v[210:213], v[16:19]
	v_mfma_f32_16x16x32_bf16 v[60:63], v[158:161], v[190:193], v[60:63]
	v_mfma_f32_16x16x32_bf16 v[56:59], v[166:169], v[190:193], v[56:59]
	v_mfma_f32_16x16x32_bf16 v[52:55], v[158:161], v[198:201], v[52:55]
	v_mfma_f32_16x16x32_bf16 v[48:51], v[166:169], v[198:201], v[48:51]
	v_mfma_f32_16x16x32_bf16 v[36:39], v[158:161], v[206:209], v[36:39]
	v_mfma_f32_16x16x32_bf16 v[32:35], v[166:169], v[206:209], v[32:35]
	v_mfma_f32_16x16x32_bf16 v[20:23], v[158:161], v[214:217], v[20:23]
	v_mfma_f32_16x16x32_bf16 v[16:19], v[166:169], v[214:217], v[16:19]
	s_setprio 0
	s_setprio 1
	v_mfma_f32_16x16x32_bf16 v[44:47], v[170:173], v[186:189], v[44:47]
	v_mfma_f32_16x16x32_bf16 v[40:43], v[178:181], v[186:189], v[40:43]
	v_mfma_f32_16x16x32_bf16 v[28:31], v[170:173], v[194:197], v[28:31]
	v_mfma_f32_16x16x32_bf16 v[24:27], v[178:181], v[194:197], v[24:27]
	v_mfma_f32_16x16x32_bf16 v[12:15], v[170:173], v[202:205], v[12:15]
	v_mfma_f32_16x16x32_bf16 v[8:11], v[178:181], v[202:205], v[8:11]
	v_mfma_f32_16x16x32_bf16 v[4:7], v[170:173], v[210:213], v[4:7]
	v_mfma_f32_16x16x32_bf16 v[0:3], v[178:181], v[210:213], v[0:3]
	v_mfma_f32_16x16x32_bf16 v[44:47], v[174:177], v[190:193], v[44:47]
	v_mfma_f32_16x16x32_bf16 v[40:43], v[182:185], v[190:193], v[40:43]
	v_mfma_f32_16x16x32_bf16 v[28:31], v[174:177], v[198:201], v[28:31]
	v_mfma_f32_16x16x32_bf16 v[24:27], v[182:185], v[198:201], v[24:27]
	v_mfma_f32_16x16x32_bf16 v[12:15], v[174:177], v[206:209], v[12:15]
	v_mfma_f32_16x16x32_bf16 v[8:11], v[182:185], v[206:209], v[8:11]
	v_mfma_f32_16x16x32_bf16 v[4:7], v[174:177], v[214:217], v[4:7]
	s_barrier
	v_mfma_f32_16x16x32_bf16 v[0:3], v[182:185], v[214:217], v[0:3]
	s_setprio 0
	s_add_i32 s93, s93, 2
	s_add_u32 s68, s68, 0x100
	s_addc_u32 s69, s69, 0
	s_add_u32 s91, s91, 0x100
	s_addc_u32 s92, s92, 0
	s_cmp_gt_u32 s93, 29
	s_cbranch_scc0 .LBB0_119
	s_and_b64 vcc, exec, s[16:17]
	s_cbranch_vccz .LBB0_122
	s_barrier

; #define PG8_STAGE(bufoff, gbase, voff) do { _Pragma("unroll") for (int _i = 0; _i < 2; ++_i) \
;         __builtin_amdgcn_global_load_lds((const unsigned*)((const char*)(gbase) + (voff)[_i]), (PG8_LAS unsigned*)(lds + (bufoff) + ldsw + _i * 8192), 16, 0, 0); } while (0)
; #define PG8_LDA(dst, b, h) do { _Pragma("unroll") for (int m = 0; m < 4; ++m) _Pragma("unroll") for (int k = 0; k < 2; ++k) dst[m][k] = *(const PG8_LAS bf16x8*)(lds + PG8_SA(b, h) + aoff + m * 2048 + k * 1024); } while (0)
; #define PG8_LDB(dst, b, h) do { _Pragma("unroll") for (int n = 0; n < 2; ++n) _Pragma("unroll") for (int k = 0; k < 2; ++k) dst[n][k] = *(const PG8_LAS bf16x8*)(lds + PG8_SB(b, h) + boff + n * 2048 + k * 1024); } while (0)
; #define PG8_MMA(ai, bj, At, Bt) do { __builtin_amdgcn_s_setprio(1); _Pragma("unroll") for (int m = 0; m < 4; ++m) _Pragma("unroll") for (int n = 0; n < 2; ++n) _Pragma("unroll") for (int k = 0; k < 2; ++k) \
;         acc[ai][bj][m][n] = __builtin_amdgcn_mfma_f32_16x16x32_bf16(Bt[n][k], At[m][k], acc[ai][bj][m][n], 0, 0, 0); __builtin_amdgcn_s_setprio(0); } while (0)
; #define PG8_WAIT_V(n) asm volatile("s_waitcnt vmcnt(" #n ")" ::: "memory")
; #define PG8_WAIT_L(n) asm volatile("s_waitcnt lgkmcnt(" #n ")" ::: "memory")
; template <class Epi, class Sched, bool ALIGN_EPI = false, bool SP2 = false>
; __device__ __forceinline__ void gemm_phase(PG8_LAS unsigned char* lds, const Gemm g, const Sched& S, const Epi& E) {
;     ...
;             const bool last = (t == nt - 2);
;             const char* a1 = cA + (size_t)(t + 1) * kstep;
;             const char* a2 = last ? nA : cA + (size_t)(t + 2) * kstep; const char* b2 = last ? nB : cB + (size_t)(t + 2) * kstep;
;             const char* a3 = a2 + kstep; const char* b3 = b2 + kstep;
;             if (last && has_next) S.a_ready(nxt);
;             if constexpr (SP2) {
;             PG8_LDB(B0, 0, 0); PG8_LDB(B1, 0, 1); PG8_SCHED; PG8_LDA(At, 0, 0); PG8_STAGE(PG8_SA(1, 1), a1 + hstep, voffA);
;             PG8_WAIT_V(8); PG8_WAIT_L(0); PG8_BAR; PG8_MMA(0, 0, At, B0); PG8_MMA(0, 1, At, B1); PG8_BAR; PG8_SCHED;
;             PG8_LDA(At, 0, 1); PG8_STAGE(PG8_SB(0, 0), b2, voffB); PG8_STAGE(PG8_SB(0, 1), b2 + hstep, voffB); PG8_STAGE(PG8_SA(0, 0), a2, voffA);
;             PG8_WAIT_V(8); PG8_WAIT_L(0); PG8_BAR; PG8_MMA(1, 0, At, B0); PG8_MMA(1, 1, At, B1); PG8_BAR; PG8_SCHED;
.LBB0_559:
	ds_read_b128 v[148:151], v145
	ds_read_b128 v[152:155], v145 offset:1024
	ds_read_b128 v[156:159], v145 offset:2048
	ds_read_b128 v[160:163], v145 offset:3072
	ds_read_b128 v[164:167], v146
	ds_read_b128 v[168:171], v146 offset:1024
	ds_read_b128 v[172:175], v146 offset:2048
	ds_read_b128 v[176:179], v146 offset:3072
	s_add_u32 s38, s36, 0x100
	s_addc_u32 s39, s37, 0
	s_cmp_eq_u32 s85, 28
	s_cselect_b32 s67, s25, s39
	s_cselect_b32 s66, s81, s38
	s_cselect_b32 s45, s23, s84
	s_cselect_b32 s44, s82, s83
	v_lshl_add_u64 v[140:141], s[36:37], 0, v[132:133]
	s_add_i32 m0, s68, 0xc000
	ds_read_b128 v[180:183], v147
	ds_read_b128 v[184:187], v147 offset:1024
	ds_read_b128 v[188:191], v147 offset:2048
	ds_read_b128 v[192:195], v147 offset:3072
	ds_read_b128 v[196:199], v147 offset:4096
	ds_read_b128 v[200:203], v147 offset:5120
	ds_read_b128 v[204:207], v147 offset:6144
	ds_read_b128 v[208:211], v147 offset:7168
	global_load_lds_dwordx4 v[140:141], off
	v_lshl_add_u64 v[140:141], s[36:37], 0, v[134:135]
	s_add_i32 m0, s68, 0xe000
	s_nop 0
	global_load_lds_dwordx4 v[140:141], off
	s_waitcnt vmcnt(8)
	s_waitcnt lgkmcnt(0)
	s_barrier
	s_setprio 1
	s_waitcnt lgkmcnt(0)
	v_mfma_f32_16x16x32_bf16 v[124:127], v[148:151], v[180:183], v[124:127]
	v_mfma_f32_16x16x32_bf16 v[120:123], v[156:159], v[180:183], v[120:123]
	v_mfma_f32_16x16x32_bf16 v[112:115], v[148:151], v[188:191], v[112:115]
	v_mfma_f32_16x16x32_bf16 v[108:111], v[156:159], v[188:191], v[108:111]
	v_mfma_f32_16x16x32_bf16 v[96:99], v[148:151], v[196:199], v[96:99]
	v_mfma_f32_16x16x32_bf16 v[92:95], v[156:159], v[196:199], v[92:95]
	v_mfma_f32_16x16x32_bf16 v[80:83], v[148:151], v[204:207], v[80:83]
	v_mfma_f32_16x16x32_bf16 v[76:79], v[156:159], v[204:207], v[76:79]
	v_mfma_f32_16x16x32_bf16 v[124:127], v[152:155], v[184:187], v[124:127]
	v_mfma_f32_16x16x32_bf16 v[120:123], v[160:163], v[184:187], v[120:123]
	v_mfma_f32_16x16x32_bf16 v[112:115], v[152:155], v[192:195], v[112:115]
	v_mfma_f32_16x16x32_bf16 v[108:111], v[160:163], v[192:195], v[108:111]
	v_mfma_f32_16x16x32_bf16 v[96:99], v[152:155], v[200:203], v[96:99]
	v_mfma_f32_16x16x32_bf16 v[92:95], v[160:163], v[200:203], v[92:95]
	v_mfma_f32_16x16x32_bf16 v[80:83], v[152:155], v[208:211], v[80:83]
	v_mfma_f32_16x16x32_bf16 v[76:79], v[160:163], v[208:211], v[76:79]
	s_setprio 0
	s_setprio 1
	v_mfma_f32_16x16x32_bf16 v[116:119], v[164:167], v[180:183], v[116:119]
	v_mfma_f32_16x16x32_bf16 v[104:107], v[172:175], v[180:183], v[104:107]
	v_mfma_f32_16x16x32_bf16 v[100:103], v[164:167], v[188:191], v[100:103]
	v_mfma_f32_16x16x32_bf16 v[88:91], v[172:175], v[188:191], v[88:91]
	v_mfma_f32_16x16x32_bf16 v[84:87], v[164:167], v[196:199], v[84:87]
	v_mfma_f32_16x16x32_bf16 v[72:75], v[172:175], v[196:199], v[72:75]
	v_mfma_f32_16x16x32_bf16 v[68:71], v[164:167], v[204:207], v[68:71]
	v_mfma_f32_16x16x32_bf16 v[64:67], v[172:175], v[204:207], v[64:67]
	v_mfma_f32_16x16x32_bf16 v[116:119], v[168:171], v[184:187], v[116:119]
	v_mfma_f32_16x16x32_bf16 v[104:107], v[176:179], v[184:187], v[104:107]
	v_mfma_f32_16x16x32_bf16 v[100:103], v[168:171], v[192:195], v[100:103]
	v_mfma_f32_16x16x32_bf16 v[88:91], v[176:179], v[192:195], v[88:91]
	v_mfma_f32_16x16x32_bf16 v[84:87], v[168:171], v[200:203], v[84:87]
	v_mfma_f32_16x16x32_bf16 v[72:75], v[176:179], v[200:203], v[72:75]
	v_mfma_f32_16x16x32_bf16 v[68:71], v[168:171], v[208:211], v[68:71]
	s_barrier
	v_mfma_f32_16x16x32_bf16 v[64:67], v[176:179], v[208:211], v[64:67]
	s_setprio 0
	s_add_i32 s36, s79, s3
	v_lshl_add_u64 v[140:141], s[44:45], 0, v[130:131]
	s_mov_b32 m0, s36
	ds_read_b128 v[180:183], v147 offset:16384
	ds_read_b128 v[184:187], v147 offset:17408
	ds_read_b128 v[188:191], v147 offset:18432
	ds_read_b128 v[192:195], v147 offset:19456
	ds_read_b128 v[196:199], v147 offset:20480
	ds_read_b128 v[200:203], v147 offset:21504
	ds_read_b128 v[204:207], v147 offset:22528
	ds_read_b128 v[208:211], v147 offset:23552
	global_load_lds_dwordx4 v[140:141], off
	s_add_i32 m0, s36, 0x2000
	s_add_u32 s36, s44, 0x80000
	v_lshl_add_u64 v[212:213], s[44:45], 0, v[128:129]
	s_addc_u32 s37, s45, 0
	s_add_i32 s86, s80, s3
	global_load_lds_dwordx4 v[212:213], off
	v_lshl_add_u64 v[214:215], s[36:37], 0, v[130:131]
	s_mov_b32 m0, s86
	v_lshl_add_u64 v[216:217], s[66:67], 0, v[128:129]
	global_load_lds_dwordx4 v[214:215], off
	v_lshl_add_u64 v[214:215], s[36:37], 0, v[128:129]
	s_add_i32 m0, s86, 0x2000
	s_nop 0
	global_load_lds_dwordx4 v[214:215], off
	v_lshl_add_u64 v[214:215], s[66:67], 0, v[130:131]
	s_mov_b32 m0, s68
	s_nop 0
	global_load_lds_dwordx4 v[214:215], off
	s_mov_b32 m0, s69
	s_nop 0
	global_load_lds_dwordx4 v[216:217], off
	s_waitcnt vmcnt(8)
	s_waitcnt lgkmcnt(0)
	s_barrier
; #define PG8_STAGE(bufoff, gbase, voff) do { _Pragma("unroll") for (int _i = 0; _i < 2; ++_i) \
;         __builtin_amdgcn_global_load_lds((const unsigned*)((const char*)(gbase) + (voff)[_i]), (PG8_LAS unsigned*)(lds + (bufoff) + ldsw + _i * 8192), 16, 0, 0); } while (0)
; #define PG8_LDA(dst, b, h) do { _Pragma("unroll") for (int m = 0; m < 4; ++m) _Pragma("unroll") for (int k = 0; k < 2; ++k) dst[m][k] = *(const PG8_LAS bf16x8*)(lds + PG8_SA(b, h) + aoff + m * 2048 + k * 1024); } while (0)
; #define PG8_LDB(dst, b, h) do { _Pragma("unroll") for (int n = 0; n < 2; ++n) _Pragma("unroll") for (int k = 0; k < 2; ++k) dst[n][k] = *(const PG8_LAS bf16x8*)(lds + PG8_SB(b, h) + boff + n * 2048 + k * 1024); } while (0)
; #define PG8_MMA(ai, bj, At, Bt) do { __builtin_amdgcn_s_setprio(1); _Pragma("unroll") for (int m = 0; m < 4; ++m) _Pragma("unroll") for (int n = 0; n < 2; ++n) _Pragma("unroll") for (int k = 0; k < 2; ++k) \
;         acc[ai][bj][m][n] = __builtin_amdgcn_mfma_f32_16x16x32_bf16(Bt[n][k], At[m][k], acc[ai][bj][m][n], 0, 0, 0); __builtin_amdgcn_s_setprio(0); } while (0)
; #define PG8_WAIT_V(n) asm volatile("s_waitcnt vmcnt(" #n ")" ::: "memory")
; #define PG8_WAIT_L(n) asm volatile("s_waitcnt lgkmcnt(" #n ")" ::: "memory")
; #define PG8_BAR __builtin_amdgcn_s_barrier()
; #define PG8_SCHED __builtin_amdgcn_sched_barrier(0)
; template <class Epi, class Sched, bool ALIGN_EPI = false, bool SP2 = false>
; __device__ __forceinline__ void gemm_phase(PG8_LAS unsigned char* lds, const Gemm g, const Sched& S, const Epi& E) {
;     ...
;             PG8_WAIT_V(8); PG8_WAIT_L(0); PG8_BAR; PG8_MMA(0, 0, At, B0); PG8_MMA(0, 1, At, B1); PG8_BAR; PG8_SCHED;
;             PG8_LDA(At, 0, 1); PG8_STAGE(PG8_SB(0, 0), b2, voffB); PG8_STAGE(PG8_SB(0, 1), b2 + hstep, voffB); PG8_STAGE(PG8_SA(0, 0), a2, voffA);
;             PG8_WAIT_V(8); PG8_WAIT_L(0); PG8_BAR; PG8_MMA(1, 0, At, B0); PG8_MMA(1, 1, At, B1); PG8_BAR; PG8_SCHED;
;             PG8_LDB(B0, 1, 0); PG8_LDB(B1, 1, 1); PG8_SCHED; PG8_LDA(At, 1, 0); PG8_STAGE(PG8_SA(0, 1), a2 + hstep, voffA);
;             PG8_WAIT_V(8); PG8_WAIT_L(0); PG8_BAR; PG8_MMA(0, 0, At, B0); PG8_MMA(0, 1, At, B1); PG8_BAR; PG8_SCHED;
	s_setprio 1
	s_waitcnt lgkmcnt(0)
	v_mfma_f32_16x16x32_bf16 v[60:63], v[148:151], v[180:183], v[60:63]
	v_mfma_f32_16x16x32_bf16 v[56:59], v[156:159], v[180:183], v[56:59]
	v_mfma_f32_16x16x32_bf16 v[48:51], v[148:151], v[188:191], v[48:51]
	v_mfma_f32_16x16x32_bf16 v[44:47], v[156:159], v[188:191], v[44:47]
	v_mfma_f32_16x16x32_bf16 v[32:35], v[148:151], v[196:199], v[32:35]
	v_mfma_f32_16x16x32_bf16 v[28:31], v[156:159], v[196:199], v[28:31]
	v_mfma_f32_16x16x32_bf16 v[16:19], v[148:151], v[204:207], v[16:19]
	v_mfma_f32_16x16x32_bf16 v[12:15], v[156:159], v[204:207], v[12:15]
	v_mfma_f32_16x16x32_bf16 v[60:63], v[152:155], v[184:187], v[60:63]
	v_mfma_f32_16x16x32_bf16 v[56:59], v[160:163], v[184:187], v[56:59]
	v_mfma_f32_16x16x32_bf16 v[48:51], v[152:155], v[192:195], v[48:51]
	v_mfma_f32_16x16x32_bf16 v[44:47], v[160:163], v[192:195], v[44:47]
	v_mfma_f32_16x16x32_bf16 v[32:35], v[152:155], v[200:203], v[32:35]
	v_mfma_f32_16x16x32_bf16 v[28:31], v[160:163], v[200:203], v[28:31]
	v_mfma_f32_16x16x32_bf16 v[16:19], v[152:155], v[208:211], v[16:19]
	v_mfma_f32_16x16x32_bf16 v[12:15], v[160:163], v[208:211], v[12:15]
	s_setprio 0
	s_setprio 1
	v_mfma_f32_16x16x32_bf16 v[52:55], v[164:167], v[180:183], v[52:55]
	v_mfma_f32_16x16x32_bf16 v[40:43], v[172:175], v[180:183], v[40:43]
	v_mfma_f32_16x16x32_bf16 v[36:39], v[164:167], v[188:191], v[36:39]
	v_mfma_f32_16x16x32_bf16 v[24:27], v[172:175], v[188:191], v[24:27]
	v_mfma_f32_16x16x32_bf16 v[20:23], v[164:167], v[196:199], v[20:23]
	v_mfma_f32_16x16x32_bf16 v[8:11], v[172:175], v[196:199], v[8:11]
	v_mfma_f32_16x16x32_bf16 v[4:7], v[164:167], v[204:207], v[4:7]
	v_mfma_f32_16x16x32_bf16 v[0:3], v[172:175], v[204:207], v[0:3]
	v_mfma_f32_16x16x32_bf16 v[52:55], v[168:171], v[184:187], v[52:55]
	v_mfma_f32_16x16x32_bf16 v[40:43], v[176:179], v[184:187], v[40:43]
	v_mfma_f32_16x16x32_bf16 v[36:39], v[168:171], v[192:195], v[36:39]
	v_mfma_f32_16x16x32_bf16 v[24:27], v[176:179], v[192:195], v[24:27]
	v_mfma_f32_16x16x32_bf16 v[20:23], v[168:171], v[200:203], v[20:23]
	v_mfma_f32_16x16x32_bf16 v[8:11], v[176:179], v[200:203], v[8:11]
	v_mfma_f32_16x16x32_bf16 v[4:7], v[168:171], v[208:211], v[4:7]
	s_barrier
	v_mfma_f32_16x16x32_bf16 v[0:3], v[176:179], v[208:211], v[0:3]
	s_setprio 0
	s_add_i32 s86, 0, 0x18000
	s_add_i32 s87, 0, 0x1c000
	v_add_u32_e32 v160, s86, v143
	v_add_u32_e32 v176, s87, v143
	ds_read_b128 v[148:151], v160
	ds_read_b128 v[152:155], v160 offset:1024
	ds_read_b128 v[156:159], v160 offset:2048
	ds_read_b128 v[160:163], v160 offset:3072
	ds_read_b128 v[164:167], v176
	ds_read_b128 v[168:171], v176 offset:1024
	ds_read_b128 v[172:175], v176 offset:2048
	ds_read_b128 v[176:179], v176 offset:3072
	s_add_u32 s36, s66, 0x80000
	s_addc_u32 s37, s67, 0
	s_mov_b32 m0, s70
	v_lshl_add_u64 v[218:219], s[36:37], 0, v[130:131]
	ds_read_b128 v[180:183], v147 offset:32768
	ds_read_b128 v[184:187], v147 offset:33792
	ds_read_b128 v[188:191], v147 offset:34816
	ds_read_b128 v[192:195], v147 offset:35840
	ds_read_b128 v[196:199], v147 offset:36864
	ds_read_b128 v[200:203], v147 offset:37888
	ds_read_b128 v[204:207], v147 offset:38912
	ds_read_b128 v[208:211], v147 offset:39936
	global_load_lds_dwordx4 v[218:219], off
	v_lshl_add_u64 v[218:219], s[36:37], 0, v[128:129]
	s_mov_b32 m0, s71
	s_nop 0
	global_load_lds_dwordx4 v[218:219], off
	s_waitcnt vmcnt(8)
	s_waitcnt lgkmcnt(0)
	s_barrier
	s_setprio 1
	s_waitcnt lgkmcnt(0)
	v_mfma_f32_16x16x32_bf16 v[124:127], v[148:151], v[180:183], v[124:127]
	v_mfma_f32_16x16x32_bf16 v[120:123], v[156:159], v[180:183], v[120:123]
	v_mfma_f32_16x16x32_bf16 v[112:115], v[148:151], v[188:191], v[112:115]
	v_mfma_f32_16x16x32_bf16 v[108:111], v[156:159], v[188:191], v[108:111]
	v_mfma_f32_16x16x32_bf16 v[96:99], v[148:151], v[196:199], v[96:99]
	v_mfma_f32_16x16x32_bf16 v[92:95], v[156:159], v[196:199], v[92:95]
	v_mfma_f32_16x16x32_bf16 v[80:83], v[148:151], v[204:207], v[80:83]
	v_mfma_f32_16x16x32_bf16 v[76:79], v[156:159], v[204:207], v[76:79]
	v_mfma_f32_16x16x32_bf16 v[124:127], v[152:155], v[184:187], v[124:127]
	v_mfma_f32_16x16x32_bf16 v[120:123], v[160:163], v[184:187], v[120:123]
	v_mfma_f32_16x16x32_bf16 v[112:115], v[152:155], v[192:195], v[112:115]
	v_mfma_f32_16x16x32_bf16 v[108:111], v[160:163], v[192:195], v[108:111]
	v_mfma_f32_16x16x32_bf16 v[96:99], v[152:155], v[200:203], v[96:99]
	v_mfma_f32_16x16x32_bf16 v[92:95], v[160:163], v[200:203], v[92:95]
	v_mfma_f32_16x16x32_bf16 v[80:83], v[152:155], v[208:211], v[80:83]
	v_mfma_f32_16x16x32_bf16 v[76:79], v[160:163], v[208:211], v[76:79]
	s_setprio 0
	s_setprio 1
	v_mfma_f32_16x16x32_bf16 v[116:119], v[164:167], v[180:183], v[116:119]
	v_mfma_f32_16x16x32_bf16 v[104:107], v[172:175], v[180:183], v[104:107]
	v_mfma_f32_16x16x32_bf16 v[100:103], v[164:167], v[188:191], v[100:103]
	v_mfma_f32_16x16x32_bf16 v[88:91], v[172:175], v[188:191], v[88:91]
	v_mfma_f32_16x16x32_bf16 v[84:87], v[164:167], v[196:199], v[84:87]
	v_mfma_f32_16x16x32_bf16 v[72:75], v[172:175], v[196:199], v[72:75]
	v_mfma_f32_16x16x32_bf16 v[68:71], v[164:167], v[204:207], v[68:71]
	v_mfma_f32_16x16x32_bf16 v[64:67], v[172:175], v[204:207], v[64:67]
	v_mfma_f32_16x16x32_bf16 v[116:119], v[168:171], v[184:187], v[116:119]
	v_mfma_f32_16x16x32_bf16 v[104:107], v[176:179], v[184:187], v[104:107]
	v_mfma_f32_16x16x32_bf16 v[100:103], v[168:171], v[192:195], v[100:103]
	v_mfma_f32_16x16x32_bf16 v[88:91], v[176:179], v[192:195], v[88:91]
	v_mfma_f32_16x16x32_bf16 v[84:87], v[168:171], v[200:203], v[84:87]
	v_mfma_f32_16x16x32_bf16 v[72:75], v[176:179], v[200:203], v[72:75]
	v_mfma_f32_16x16x32_bf16 v[68:71], v[168:171], v[208:211], v[68:71]
	s_barrier
; #define PG8_STAGE(bufoff, gbase, voff) do { _Pragma("unroll") for (int _i = 0; _i < 2; ++_i) \
;         __builtin_amdgcn_global_load_lds((const unsigned*)((const char*)(gbase) + (voff)[_i]), (PG8_LAS unsigned*)(lds + (bufoff) + ldsw + _i * 8192), 16, 0, 0); } while (0)
; #define PG8_WAIT_V(n) asm volatile("s_waitcnt vmcnt(" #n ")" ::: "memory")
; #define PG8_WAIT_L(n) asm volatile("s_waitcnt lgkmcnt(" #n ")" ::: "memory")
; template <class Epi, class Sched, bool ALIGN_EPI = false, bool SP2 = false>
; __device__ __forceinline__ void gemm_phase(PG8_LAS unsigned char* lds, const Gemm g, const Sched& S, const Epi& E) {
;     ...
;             PG8_WAIT_V(8); PG8_WAIT_L(0); PG8_BAR; PG8_MMA(0, 0, At, B0); PG8_MMA(0, 1, At, B1); PG8_BAR; PG8_SCHED;
;             PG8_LDA(At, 1, 1); PG8_STAGE(PG8_SB(1, 0), b3, voffB); PG8_STAGE(PG8_SB(1, 1), b3 + hstep, voffB); PG8_STAGE(PG8_SA(1, 0), a3, voffA);
;             PG8_WAIT_V(8); PG8_WAIT_L(0); PG8_BAR; PG8_MMA(1, 0, At, B0); PG8_MMA(1, 1, At, B1); PG8_BAR; PG8_SCHED;
;             } else {
;             PG8_LDB(B0, 0, 0); PG8_SCHED; PG8_LDA(At, 0, 0); PG8_STAGE(PG8_SA(1, 1), a1 + hstep, voffA);
;             PG8_WAIT_L(8); PG8_BAR; PG8_WAIT_L(0); PG8_MMA(0, 0, At, B0); PG8_BAR; PG8_SCHED;
;             PG8_LDB(B1, 0, 1); PG8_STAGE(PG8_SB(0, 0), b2, voffB);
;             PG8_BAR; PG8_WAIT_L(0); PG8_MMA(0, 1, At, B1); PG8_BAR;
;             PG8_LDA(At, 0, 1); PG8_STAGE(PG8_SA(0, 0), a2, voffA);
;             PG8_BAR; PG8_WAIT_L(0); PG8_MMA(1, 0, At, B0); PG8_BAR; PG8_SCHED;
;             PG8_STAGE(PG8_SB(0, 1), b2 + hstep, voffB);
;             PG8_WAIT_V(6); PG8_BAR; PG8_MMA(1, 1, At, B1); PG8_BAR;
;             PG8_LDB(B0, 1, 0); PG8_SCHED; PG8_LDA(At, 1, 0); PG8_STAGE(PG8_SA(0, 1), a2 + hstep, voffA);
;             PG8_WAIT_L(8); PG8_BAR; PG8_WAIT_L(0); PG8_MMA(0, 0, At, B0); PG8_BAR; PG8_SCHED;
;             PG8_LDB(B1, 1, 1); PG8_STAGE(PG8_SB(1, 0), b3, voffB);
;             PG8_BAR; PG8_WAIT_L(0); PG8_MMA(0, 1, At, B1); PG8_BAR;
;             PG8_LDA(At, 1, 1); PG8_STAGE(PG8_SA(1, 0), a3, voffA);
;             PG8_BAR; PG8_WAIT_L(0); PG8_MMA(1, 0, At, B0); PG8_BAR; PG8_SCHED;
;             PG8_STAGE(PG8_SB(1, 1), b3 + hstep, voffB);
;             PG8_WAIT_V(6); PG8_BAR; PG8_MMA(1, 1, At, B1); PG8_BAR;
;             }
;         }
;         if constexpr (ALIGN_EPI) { if (wr == 0) PG8_BAR; }
	v_mfma_f32_16x16x32_bf16 v[64:67], v[176:179], v[208:211], v[64:67]
	s_setprio 0
	s_add_i32 s36, s86, s3
	v_lshl_add_u64 v[140:141], v[140:141], 0, s[8:9]
	s_mov_b32 m0, s36
	ds_read_b128 v[180:183], v147 offset:49152
	ds_read_b128 v[184:187], v147 offset:50176
	ds_read_b128 v[188:191], v147 offset:51200
	ds_read_b128 v[192:195], v147 offset:52224
	ds_read_b128 v[196:199], v147 offset:53248
	ds_read_b128 v[200:203], v147 offset:54272
	ds_read_b128 v[204:207], v147 offset:55296
	ds_read_b128 v[208:211], v147 offset:56320
	global_load_lds_dwordx4 v[140:141], off
	s_add_i32 m0, s36, 0x2000
	s_add_u32 s36, s44, 0x80080
	v_lshl_add_u64 v[140:141], v[212:213], 0, s[8:9]
	s_addc_u32 s37, s45, 0
	s_add_i32 s44, s87, s3
	global_load_lds_dwordx4 v[140:141], off
	v_lshl_add_u64 v[140:141], s[36:37], 0, v[130:131]
	s_mov_b32 m0, s44
	s_nop 0
	global_load_lds_dwordx4 v[140:141], off
	v_lshl_add_u64 v[140:141], s[36:37], 0, v[128:129]
	s_add_i32 m0, s44, 0x2000
	s_nop 0
	global_load_lds_dwordx4 v[140:141], off
	v_lshl_add_u64 v[140:141], v[214:215], 0, s[8:9]
	s_mov_b32 m0, s75
	s_nop 0
	global_load_lds_dwordx4 v[140:141], off
	v_lshl_add_u64 v[140:141], v[216:217], 0, s[8:9]
	s_mov_b32 m0, s76
	s_nop 0
	global_load_lds_dwordx4 v[140:141], off
	s_waitcnt vmcnt(8)
	s_waitcnt lgkmcnt(0)
	s_barrier
	s_setprio 1
	s_waitcnt lgkmcnt(0)
	v_mfma_f32_16x16x32_bf16 v[60:63], v[148:151], v[180:183], v[60:63]
	v_mfma_f32_16x16x32_bf16 v[56:59], v[156:159], v[180:183], v[56:59]
	v_mfma_f32_16x16x32_bf16 v[48:51], v[148:151], v[188:191], v[48:51]
	v_mfma_f32_16x16x32_bf16 v[44:47], v[156:159], v[188:191], v[44:47]
	v_mfma_f32_16x16x32_bf16 v[32:35], v[148:151], v[196:199], v[32:35]
	v_mfma_f32_16x16x32_bf16 v[28:31], v[156:159], v[196:199], v[28:31]
	v_mfma_f32_16x16x32_bf16 v[16:19], v[148:151], v[204:207], v[16:19]
	v_mfma_f32_16x16x32_bf16 v[12:15], v[156:159], v[204:207], v[12:15]
	v_mfma_f32_16x16x32_bf16 v[60:63], v[152:155], v[184:187], v[60:63]
	v_mfma_f32_16x16x32_bf16 v[56:59], v[160:163], v[184:187], v[56:59]
	v_mfma_f32_16x16x32_bf16 v[48:51], v[152:155], v[192:195], v[48:51]
	v_mfma_f32_16x16x32_bf16 v[44:47], v[160:163], v[192:195], v[44:47]
	v_mfma_f32_16x16x32_bf16 v[32:35], v[152:155], v[200:203], v[32:35]
	v_mfma_f32_16x16x32_bf16 v[28:31], v[160:163], v[200:203], v[28:31]
	v_mfma_f32_16x16x32_bf16 v[16:19], v[152:155], v[208:211], v[16:19]
	v_mfma_f32_16x16x32_bf16 v[12:15], v[160:163], v[208:211], v[12:15]
	s_setprio 0
	s_setprio 1
	v_mfma_f32_16x16x32_bf16 v[52:55], v[164:167], v[180:183], v[52:55]
	v_mfma_f32_16x16x32_bf16 v[40:43], v[172:175], v[180:183], v[40:43]
	v_mfma_f32_16x16x32_bf16 v[36:39], v[164:167], v[188:191], v[36:39]
	v_mfma_f32_16x16x32_bf16 v[24:27], v[172:175], v[188:191], v[24:27]
	v_mfma_f32_16x16x32_bf16 v[20:23], v[164:167], v[196:199], v[20:23]
	v_mfma_f32_16x16x32_bf16 v[8:11], v[172:175], v[196:199], v[8:11]
	v_mfma_f32_16x16x32_bf16 v[4:7], v[164:167], v[204:207], v[4:7]
	v_mfma_f32_16x16x32_bf16 v[0:3], v[172:175], v[204:207], v[0:3]
	v_mfma_f32_16x16x32_bf16 v[52:55], v[168:171], v[184:187], v[52:55]
	v_mfma_f32_16x16x32_bf16 v[40:43], v[176:179], v[184:187], v[40:43]
	v_mfma_f32_16x16x32_bf16 v[36:39], v[168:171], v[192:195], v[36:39]
	v_mfma_f32_16x16x32_bf16 v[24:27], v[176:179], v[192:195], v[24:27]
	v_mfma_f32_16x16x32_bf16 v[20:23], v[168:171], v[200:203], v[20:23]
	v_mfma_f32_16x16x32_bf16 v[8:11], v[176:179], v[200:203], v[8:11]
	v_mfma_f32_16x16x32_bf16 v[4:7], v[168:171], v[208:211], v[4:7]
	s_barrier
	v_mfma_f32_16x16x32_bf16 v[0:3], v[176:179], v[208:211], v[0:3]
	s_setprio 0
	s_add_i32 s85, s85, 2
	s_add_u32 s83, s83, 0x100
	s_addc_u32 s84, s84, 0
	s_cmp_gt_u32 s85, 29
	s_mov_b64 s[36:37], s[38:39]
	s_cbranch_scc0 .LBB0_559
	s_and_b64 vcc, exec, s[10:11]
	s_cbranch_vccz .LBB0_562
	s_barrier

; #define PG8_STAGE(bufoff, gbase, voff) do { _Pragma("unroll") for (int _i = 0; _i < 2; ++_i) \
;         __builtin_amdgcn_global_load_lds((const unsigned*)((const char*)(gbase) + (voff)[_i]), (PG8_LAS unsigned*)(lds + (bufoff) + ldsw + _i * 8192), 16, 0, 0); } while (0)
; #define PG8_LDA(dst, b, h) do { _Pragma("unroll") for (int m = 0; m < 4; ++m) _Pragma("unroll") for (int k = 0; k < 2; ++k) dst[m][k] = *(const PG8_LAS bf16x8*)(lds + PG8_SA(b, h) + aoff + m * 2048 + k * 1024); } while (0)
; #define PG8_LDB(dst, b, h) do { _Pragma("unroll") for (int n = 0; n < 2; ++n) _Pragma("unroll") for (int k = 0; k < 2; ++k) dst[n][k] = *(const PG8_LAS bf16x8*)(lds + PG8_SB(b, h) + boff + n * 2048 + k * 1024); } while (0)
; #define PG8_MMA(ai, bj, At, Bt) do { __builtin_amdgcn_s_setprio(1); _Pragma("unroll") for (int m = 0; m < 4; ++m) _Pragma("unroll") for (int n = 0; n < 2; ++n) _Pragma("unroll") for (int k = 0; k < 2; ++k) \
;         acc[ai][bj][m][n] = __builtin_amdgcn_mfma_f32_16x16x32_bf16(Bt[n][k], At[m][k], acc[ai][bj][m][n], 0, 0, 0); __builtin_amdgcn_s_setprio(0); } while (0)
; #define PG8_WAIT_V(n) asm volatile("s_waitcnt vmcnt(" #n ")" ::: "memory")
; #define PG8_WAIT_L(n) asm volatile("s_waitcnt lgkmcnt(" #n ")" ::: "memory")
; template <class Epi, class Sched, bool ALIGN_EPI = false, bool SP2 = false>
; __device__ __forceinline__ void gemm_phase(PG8_LAS unsigned char* lds, const Gemm g, const Sched& S, const Epi& E) {
;     ...
;             const bool last = (t == nt - 2);
;             const char* a1 = cA + (size_t)(t + 1) * kstep;
;             const char* a2 = last ? nA : cA + (size_t)(t + 2) * kstep; const char* b2 = last ? nB : cB + (size_t)(t + 2) * kstep;
;             const char* a3 = a2 + kstep; const char* b3 = b2 + kstep;
;             if (last && has_next) S.a_ready(nxt);
;             if constexpr (SP2) {
;             PG8_LDB(B0, 0, 0); PG8_LDB(B1, 0, 1); PG8_SCHED; PG8_LDA(At, 0, 0); PG8_STAGE(PG8_SA(1, 1), a1 + hstep, voffA);
;             PG8_WAIT_V(8); PG8_WAIT_L(0); PG8_BAR; PG8_MMA(0, 0, At, B0); PG8_MMA(0, 1, At, B1); PG8_BAR; PG8_SCHED;
;             PG8_LDA(At, 0, 1); PG8_STAGE(PG8_SB(0, 0), b2, voffB); PG8_STAGE(PG8_SB(0, 1), b2 + hstep, voffB); PG8_STAGE(PG8_SA(0, 0), a2, voffA);
;             PG8_WAIT_V(8); PG8_WAIT_L(0); PG8_BAR; PG8_MMA(1, 0, At, B0); PG8_MMA(1, 1, At, B1); PG8_BAR; PG8_SCHED;
.LBB0_704:
	s_add_u32 s10, s8, 0xfff80080
	s_addc_u32 s11, s9, -1
	s_add_i32 s35, 0, 0x10000
	s_cmp_eq_u32 s34, 28
	s_cselect_b32 s13, s31, s11
	s_cselect_b32 s12, s74, s10
	v_add_u32_e32 v142, s35, v146
	s_cselect_b32 s11, s39, vcc_hi
	s_cselect_b32 s10, s89, vcc_lo
	s_add_i32 s54, 0, 0x14000
	ds_read_b128 v[150:153], v142
	ds_read_b128 v[154:157], v142 offset:1024
	ds_read_b128 v[158:161], v142 offset:2048
	ds_read_b128 v[162:165], v142 offset:3072
	v_add_u32_e32 v142, s54, v146
	ds_read_b128 v[166:169], v142
	ds_read_b128 v[170:173], v142 offset:1024
	ds_read_b128 v[174:177], v142 offset:2048
	ds_read_b128 v[178:181], v142 offset:3072
	v_lshl_add_u64 v[142:143], s[8:9], 0, v[136:137]
	s_add_i32 m0, s25, 0xc000
	ds_read_b128 v[182:185], v148
	ds_read_b128 v[186:189], v148 offset:1024
	ds_read_b128 v[190:193], v148 offset:2048
	ds_read_b128 v[194:197], v148 offset:3072
	ds_read_b128 v[198:201], v148 offset:4096
	ds_read_b128 v[202:205], v148 offset:5120
	ds_read_b128 v[206:209], v148 offset:6144
	ds_read_b128 v[210:213], v148 offset:7168
	global_load_lds_dwordx4 v[142:143], off
	v_lshl_add_u64 v[142:143], s[8:9], 0, v[138:139]
	s_add_i32 m0, s25, 0xe000
	s_nop 0
	global_load_lds_dwordx4 v[142:143], off
	s_waitcnt vmcnt(8)
	s_waitcnt lgkmcnt(0)
	s_barrier
	s_setprio 1
	s_waitcnt lgkmcnt(0)
	v_mfma_f32_16x16x32_bf16 v[124:127], v[150:153], v[182:185], v[124:127]
	v_mfma_f32_16x16x32_bf16 v[120:123], v[158:161], v[182:185], v[120:123]
	v_mfma_f32_16x16x32_bf16 v[108:111], v[150:153], v[190:193], v[108:111]
	v_mfma_f32_16x16x32_bf16 v[104:107], v[158:161], v[190:193], v[104:107]
	v_mfma_f32_16x16x32_bf16 v[92:95], v[150:153], v[198:201], v[92:95]
	v_mfma_f32_16x16x32_bf16 v[88:91], v[158:161], v[198:201], v[88:91]
	v_mfma_f32_16x16x32_bf16 v[76:79], v[150:153], v[206:209], v[76:79]
	v_mfma_f32_16x16x32_bf16 v[72:75], v[158:161], v[206:209], v[72:75]
	v_mfma_f32_16x16x32_bf16 v[124:127], v[154:157], v[186:189], v[124:127]
	v_mfma_f32_16x16x32_bf16 v[120:123], v[162:165], v[186:189], v[120:123]
	v_mfma_f32_16x16x32_bf16 v[108:111], v[154:157], v[194:197], v[108:111]
	v_mfma_f32_16x16x32_bf16 v[104:107], v[162:165], v[194:197], v[104:107]
	v_mfma_f32_16x16x32_bf16 v[92:95], v[154:157], v[202:205], v[92:95]
	v_mfma_f32_16x16x32_bf16 v[88:91], v[162:165], v[202:205], v[88:91]
	v_mfma_f32_16x16x32_bf16 v[76:79], v[154:157], v[210:213], v[76:79]
	v_mfma_f32_16x16x32_bf16 v[72:75], v[162:165], v[210:213], v[72:75]
	s_setprio 0
	s_setprio 1
	v_mfma_f32_16x16x32_bf16 v[116:119], v[166:169], v[182:185], v[116:119]
	v_mfma_f32_16x16x32_bf16 v[112:115], v[174:177], v[182:185], v[112:115]
	v_mfma_f32_16x16x32_bf16 v[100:103], v[166:169], v[190:193], v[100:103]
	v_mfma_f32_16x16x32_bf16 v[96:99], v[174:177], v[190:193], v[96:99]
	v_mfma_f32_16x16x32_bf16 v[84:87], v[166:169], v[198:201], v[84:87]
	v_mfma_f32_16x16x32_bf16 v[80:83], v[174:177], v[198:201], v[80:83]
	v_mfma_f32_16x16x32_bf16 v[68:71], v[166:169], v[206:209], v[68:71]
	v_mfma_f32_16x16x32_bf16 v[64:67], v[174:177], v[206:209], v[64:67]
	v_mfma_f32_16x16x32_bf16 v[116:119], v[170:173], v[186:189], v[116:119]
	v_mfma_f32_16x16x32_bf16 v[112:115], v[178:181], v[186:189], v[112:115]
	v_mfma_f32_16x16x32_bf16 v[100:103], v[170:173], v[194:197], v[100:103]
	v_mfma_f32_16x16x32_bf16 v[96:99], v[178:181], v[194:197], v[96:99]
	v_mfma_f32_16x16x32_bf16 v[84:87], v[170:173], v[202:205], v[84:87]
	v_mfma_f32_16x16x32_bf16 v[80:83], v[178:181], v[202:205], v[80:83]
	v_mfma_f32_16x16x32_bf16 v[68:71], v[170:173], v[210:213], v[68:71]
	s_barrier
	v_mfma_f32_16x16x32_bf16 v[64:67], v[178:181], v[210:213], v[64:67]
	s_setprio 0
	s_add_i32 s35, s35, s24
	v_lshl_add_u64 v[142:143], s[10:11], 0, v[128:129]
	s_mov_b32 m0, s35
	ds_read_b128 v[182:185], v148 offset:16384
	ds_read_b128 v[186:189], v148 offset:17408
	ds_read_b128 v[190:193], v148 offset:18432
	ds_read_b128 v[194:197], v148 offset:19456
	ds_read_b128 v[198:201], v148 offset:20480
	ds_read_b128 v[202:205], v148 offset:21504
	ds_read_b128 v[206:209], v148 offset:22528
	ds_read_b128 v[210:213], v148 offset:23552
	global_load_lds_dwordx4 v[142:143], off
	s_add_i32 m0, s35, 0x2000
	s_add_u32 s80, s10, 0x80000
	v_lshl_add_u64 v[214:215], s[10:11], 0, v[134:135]
	s_addc_u32 s81, s11, 0
	s_add_i32 s35, s54, s24
	global_load_lds_dwordx4 v[214:215], off
	v_lshl_add_u64 v[216:217], s[80:81], 0, v[128:129]
	s_mov_b32 m0, s35
	v_lshl_add_u64 v[218:219], s[12:13], 0, v[132:133]
	global_load_lds_dwordx4 v[216:217], off
	v_lshl_add_u64 v[216:217], s[80:81], 0, v[134:135]
	s_add_i32 m0, s35, 0x2000
	s_nop 0
	global_load_lds_dwordx4 v[216:217], off
	v_lshl_add_u64 v[216:217], s[12:13], 0, v[130:131]
	s_mov_b32 m0, s25
	s_nop 0
	global_load_lds_dwordx4 v[216:217], off
	s_mov_b32 m0, s26
	s_nop 0
	global_load_lds_dwordx4 v[218:219], off
	s_waitcnt vmcnt(8)
	s_waitcnt lgkmcnt(0)
	s_barrier
; #define PG8_STAGE(bufoff, gbase, voff) do { _Pragma("unroll") for (int _i = 0; _i < 2; ++_i) \
;         __builtin_amdgcn_global_load_lds((const unsigned*)((const char*)(gbase) + (voff)[_i]), (PG8_LAS unsigned*)(lds + (bufoff) + ldsw + _i * 8192), 16, 0, 0); } while (0)
; #define PG8_LDA(dst, b, h) do { _Pragma("unroll") for (int m = 0; m < 4; ++m) _Pragma("unroll") for (int k = 0; k < 2; ++k) dst[m][k] = *(const PG8_LAS bf16x8*)(lds + PG8_SA(b, h) + aoff + m * 2048 + k * 1024); } while (0)
; #define PG8_LDB(dst, b, h) do { _Pragma("unroll") for (int n = 0; n < 2; ++n) _Pragma("unroll") for (int k = 0; k < 2; ++k) dst[n][k] = *(const PG8_LAS bf16x8*)(lds + PG8_SB(b, h) + boff + n * 2048 + k * 1024); } while (0)
; #define PG8_MMA(ai, bj, At, Bt) do { __builtin_amdgcn_s_setprio(1); _Pragma("unroll") for (int m = 0; m < 4; ++m) _Pragma("unroll") for (int n = 0; n < 2; ++n) _Pragma("unroll") for (int k = 0; k < 2; ++k) \
;         acc[ai][bj][m][n] = __builtin_amdgcn_mfma_f32_16x16x32_bf16(Bt[n][k], At[m][k], acc[ai][bj][m][n], 0, 0, 0); __builtin_amdgcn_s_setprio(0); } while (0)
; #define PG8_WAIT_V(n) asm volatile("s_waitcnt vmcnt(" #n ")" ::: "memory")
; #define PG8_WAIT_L(n) asm volatile("s_waitcnt lgkmcnt(" #n ")" ::: "memory")
; #define PG8_BAR __builtin_amdgcn_s_barrier()
; #define PG8_SCHED __builtin_amdgcn_sched_barrier(0)
; template <class Epi, class Sched, bool ALIGN_EPI = false, bool SP2 = false>
; __device__ __forceinline__ void gemm_phase(PG8_LAS unsigned char* lds, const Gemm g, const Sched& S, const Epi& E) {
;     ...
;             PG8_WAIT_V(8); PG8_WAIT_L(0); PG8_BAR; PG8_MMA(0, 0, At, B0); PG8_MMA(0, 1, At, B1); PG8_BAR; PG8_SCHED;
;             PG8_LDA(At, 0, 1); PG8_STAGE(PG8_SB(0, 0), b2, voffB); PG8_STAGE(PG8_SB(0, 1), b2 + hstep, voffB); PG8_STAGE(PG8_SA(0, 0), a2, voffA);
;             PG8_WAIT_V(8); PG8_WAIT_L(0); PG8_BAR; PG8_MMA(1, 0, At, B0); PG8_MMA(1, 1, At, B1); PG8_BAR; PG8_SCHED;
;             PG8_LDB(B0, 1, 0); PG8_LDB(B1, 1, 1); PG8_SCHED; PG8_LDA(At, 1, 0); PG8_STAGE(PG8_SA(0, 1), a2 + hstep, voffA);
;             PG8_WAIT_V(8); PG8_WAIT_L(0); PG8_BAR; PG8_MMA(0, 0, At, B0); PG8_MMA(0, 1, At, B1); PG8_BAR; PG8_SCHED;
	s_setprio 1
	s_waitcnt lgkmcnt(0)
	v_mfma_f32_16x16x32_bf16 v[60:63], v[150:153], v[182:185], v[60:63]
	v_mfma_f32_16x16x32_bf16 v[56:59], v[158:161], v[182:185], v[56:59]
	v_mfma_f32_16x16x32_bf16 v[44:47], v[150:153], v[190:193], v[44:47]
	v_mfma_f32_16x16x32_bf16 v[40:43], v[158:161], v[190:193], v[40:43]
	v_mfma_f32_16x16x32_bf16 v[28:31], v[150:153], v[198:201], v[28:31]
	v_mfma_f32_16x16x32_bf16 v[24:27], v[158:161], v[198:201], v[24:27]
	v_mfma_f32_16x16x32_bf16 v[12:15], v[150:153], v[206:209], v[12:15]
	v_mfma_f32_16x16x32_bf16 v[8:11], v[158:161], v[206:209], v[8:11]
	v_mfma_f32_16x16x32_bf16 v[60:63], v[154:157], v[186:189], v[60:63]
	v_mfma_f32_16x16x32_bf16 v[56:59], v[162:165], v[186:189], v[56:59]
	v_mfma_f32_16x16x32_bf16 v[44:47], v[154:157], v[194:197], v[44:47]
	v_mfma_f32_16x16x32_bf16 v[40:43], v[162:165], v[194:197], v[40:43]
	v_mfma_f32_16x16x32_bf16 v[28:31], v[154:157], v[202:205], v[28:31]
	v_mfma_f32_16x16x32_bf16 v[24:27], v[162:165], v[202:205], v[24:27]
	v_mfma_f32_16x16x32_bf16 v[12:15], v[154:157], v[210:213], v[12:15]
	v_mfma_f32_16x16x32_bf16 v[8:11], v[162:165], v[210:213], v[8:11]
	s_setprio 0
	s_setprio 1
	v_mfma_f32_16x16x32_bf16 v[52:55], v[166:169], v[182:185], v[52:55]
	v_mfma_f32_16x16x32_bf16 v[48:51], v[174:177], v[182:185], v[48:51]
	v_mfma_f32_16x16x32_bf16 v[36:39], v[166:169], v[190:193], v[36:39]
	v_mfma_f32_16x16x32_bf16 v[32:35], v[174:177], v[190:193], v[32:35]
	v_mfma_f32_16x16x32_bf16 v[20:23], v[166:169], v[198:201], v[20:23]
	v_mfma_f32_16x16x32_bf16 v[16:19], v[174:177], v[198:201], v[16:19]
	v_mfma_f32_16x16x32_bf16 v[4:7], v[166:169], v[206:209], v[4:7]
	v_mfma_f32_16x16x32_bf16 v[0:3], v[174:177], v[206:209], v[0:3]
	v_mfma_f32_16x16x32_bf16 v[52:55], v[170:173], v[186:189], v[52:55]
	v_mfma_f32_16x16x32_bf16 v[48:51], v[178:181], v[186:189], v[48:51]
	v_mfma_f32_16x16x32_bf16 v[36:39], v[170:173], v[194:197], v[36:39]
	v_mfma_f32_16x16x32_bf16 v[32:35], v[178:181], v[194:197], v[32:35]
	v_mfma_f32_16x16x32_bf16 v[20:23], v[170:173], v[202:205], v[20:23]
	v_mfma_f32_16x16x32_bf16 v[16:19], v[178:181], v[202:205], v[16:19]
	v_mfma_f32_16x16x32_bf16 v[4:7], v[170:173], v[210:213], v[4:7]
	s_barrier
	v_mfma_f32_16x16x32_bf16 v[0:3], v[178:181], v[210:213], v[0:3]
	s_setprio 0
	s_add_i32 s35, 0, 0x18000
	v_add_u32_e32 v149, s35, v146
	s_add_i32 s54, 0, 0x1c000
	ds_read_b128 v[150:153], v149
	ds_read_b128 v[154:157], v149 offset:1024
	ds_read_b128 v[158:161], v149 offset:2048
	ds_read_b128 v[162:165], v149 offset:3072
	v_add_u32_e32 v149, s54, v146
	ds_read_b128 v[166:169], v149
	ds_read_b128 v[170:173], v149 offset:1024
	ds_read_b128 v[174:177], v149 offset:2048
	ds_read_b128 v[178:181], v149 offset:3072
	s_add_u32 s12, s12, 0x80000
	s_addc_u32 s13, s13, 0
	s_mov_b32 m0, s27
	v_lshl_add_u64 v[220:221], s[12:13], 0, v[130:131]
	ds_read_b128 v[182:185], v148 offset:32768
	ds_read_b128 v[186:189], v148 offset:33792
	ds_read_b128 v[190:193], v148 offset:34816
	ds_read_b128 v[194:197], v148 offset:35840
	ds_read_b128 v[198:201], v148 offset:36864
	ds_read_b128 v[202:205], v148 offset:37888
	ds_read_b128 v[206:209], v148 offset:38912
	ds_read_b128 v[210:213], v148 offset:39936
	global_load_lds_dwordx4 v[220:221], off
	v_lshl_add_u64 v[220:221], s[12:13], 0, v[132:133]
	s_mov_b32 m0, s28
	s_nop 0
	global_load_lds_dwordx4 v[220:221], off
	s_waitcnt vmcnt(8)
	s_waitcnt lgkmcnt(0)
	s_barrier
	s_setprio 1
	s_waitcnt lgkmcnt(0)
	v_mfma_f32_16x16x32_bf16 v[124:127], v[150:153], v[182:185], v[124:127]
	v_mfma_f32_16x16x32_bf16 v[120:123], v[158:161], v[182:185], v[120:123]
	v_mfma_f32_16x16x32_bf16 v[108:111], v[150:153], v[190:193], v[108:111]
	v_mfma_f32_16x16x32_bf16 v[104:107], v[158:161], v[190:193], v[104:107]
	v_mfma_f32_16x16x32_bf16 v[92:95], v[150:153], v[198:201], v[92:95]
	v_mfma_f32_16x16x32_bf16 v[88:91], v[158:161], v[198:201], v[88:91]
	v_mfma_f32_16x16x32_bf16 v[76:79], v[150:153], v[206:209], v[76:79]
	v_mfma_f32_16x16x32_bf16 v[72:75], v[158:161], v[206:209], v[72:75]
	v_mfma_f32_16x16x32_bf16 v[124:127], v[154:157], v[186:189], v[124:127]
	v_mfma_f32_16x16x32_bf16 v[120:123], v[162:165], v[186:189], v[120:123]
	v_mfma_f32_16x16x32_bf16 v[108:111], v[154:157], v[194:197], v[108:111]
	v_mfma_f32_16x16x32_bf16 v[104:107], v[162:165], v[194:197], v[104:107]
	v_mfma_f32_16x16x32_bf16 v[92:95], v[154:157], v[202:205], v[92:95]
	v_mfma_f32_16x16x32_bf16 v[88:91], v[162:165], v[202:205], v[88:91]
	v_mfma_f32_16x16x32_bf16 v[76:79], v[154:157], v[210:213], v[76:79]
	v_mfma_f32_16x16x32_bf16 v[72:75], v[162:165], v[210:213], v[72:75]
	s_setprio 0
	s_setprio 1
	v_mfma_f32_16x16x32_bf16 v[116:119], v[166:169], v[182:185], v[116:119]
	v_mfma_f32_16x16x32_bf16 v[112:115], v[174:177], v[182:185], v[112:115]
	v_mfma_f32_16x16x32_bf16 v[100:103], v[166:169], v[190:193], v[100:103]
	v_mfma_f32_16x16x32_bf16 v[96:99], v[174:177], v[190:193], v[96:99]
	v_mfma_f32_16x16x32_bf16 v[84:87], v[166:169], v[198:201], v[84:87]
	v_mfma_f32_16x16x32_bf16 v[80:83], v[174:177], v[198:201], v[80:83]
	v_mfma_f32_16x16x32_bf16 v[68:71], v[166:169], v[206:209], v[68:71]
	v_mfma_f32_16x16x32_bf16 v[64:67], v[174:177], v[206:209], v[64:67]
	v_mfma_f32_16x16x32_bf16 v[116:119], v[170:173], v[186:189], v[116:119]
	v_mfma_f32_16x16x32_bf16 v[112:115], v[178:181], v[186:189], v[112:115]
	v_mfma_f32_16x16x32_bf16 v[100:103], v[170:173], v[194:197], v[100:103]
	v_mfma_f32_16x16x32_bf16 v[96:99], v[178:181], v[194:197], v[96:99]
	v_mfma_f32_16x16x32_bf16 v[84:87], v[170:173], v[202:205], v[84:87]
	v_mfma_f32_16x16x32_bf16 v[80:83], v[178:181], v[202:205], v[80:83]
	v_mfma_f32_16x16x32_bf16 v[68:71], v[170:173], v[210:213], v[68:71]
	s_barrier
; #define PG8_STAGE(bufoff, gbase, voff) do { _Pragma("unroll") for (int _i = 0; _i < 2; ++_i) \
;         __builtin_amdgcn_global_load_lds((const unsigned*)((const char*)(gbase) + (voff)[_i]), (PG8_LAS unsigned*)(lds + (bufoff) + ldsw + _i * 8192), 16, 0, 0); } while (0)
; #define PG8_WAIT_V(n) asm volatile("s_waitcnt vmcnt(" #n ")" ::: "memory")
; #define PG8_WAIT_L(n) asm volatile("s_waitcnt lgkmcnt(" #n ")" ::: "memory")
; template <class Epi, class Sched, bool ALIGN_EPI = false, bool SP2 = false>
; __device__ __forceinline__ void gemm_phase(PG8_LAS unsigned char* lds, const Gemm g, const Sched& S, const Epi& E) {
;     ...
;             PG8_WAIT_V(8); PG8_WAIT_L(0); PG8_BAR; PG8_MMA(0, 0, At, B0); PG8_MMA(0, 1, At, B1); PG8_BAR; PG8_SCHED;
;             PG8_LDA(At, 1, 1); PG8_STAGE(PG8_SB(1, 0), b3, voffB); PG8_STAGE(PG8_SB(1, 1), b3 + hstep, voffB); PG8_STAGE(PG8_SA(1, 0), a3, voffA);
;             PG8_WAIT_V(8); PG8_WAIT_L(0); PG8_BAR; PG8_MMA(1, 0, At, B0); PG8_MMA(1, 1, At, B1); PG8_BAR; PG8_SCHED;
;             } else {
;             PG8_LDB(B0, 0, 0); PG8_SCHED; PG8_LDA(At, 0, 0); PG8_STAGE(PG8_SA(1, 1), a1 + hstep, voffA);
;             PG8_WAIT_L(8); PG8_BAR; PG8_WAIT_L(0); PG8_MMA(0, 0, At, B0); PG8_BAR; PG8_SCHED;
;             PG8_LDB(B1, 0, 1); PG8_STAGE(PG8_SB(0, 0), b2, voffB);
;             PG8_BAR; PG8_WAIT_L(0); PG8_MMA(0, 1, At, B1); PG8_BAR;
;             PG8_LDA(At, 0, 1); PG8_STAGE(PG8_SA(0, 0), a2, voffA);
;             PG8_BAR; PG8_WAIT_L(0); PG8_MMA(1, 0, At, B0); PG8_BAR; PG8_SCHED;
;             PG8_STAGE(PG8_SB(0, 1), b2 + hstep, voffB);
;             PG8_WAIT_V(6); PG8_BAR; PG8_MMA(1, 1, At, B1); PG8_BAR;
;             PG8_LDB(B0, 1, 0); PG8_SCHED; PG8_LDA(At, 1, 0); PG8_STAGE(PG8_SA(0, 1), a2 + hstep, voffA);
;             PG8_WAIT_L(8); PG8_BAR; PG8_WAIT_L(0); PG8_MMA(0, 0, At, B0); PG8_BAR; PG8_SCHED;
;             PG8_LDB(B1, 1, 1); PG8_STAGE(PG8_SB(1, 0), b3, voffB);
;             PG8_BAR; PG8_WAIT_L(0); PG8_MMA(0, 1, At, B1); PG8_BAR;
;             PG8_LDA(At, 1, 1); PG8_STAGE(PG8_SA(1, 0), a3, voffA);
;             PG8_BAR; PG8_WAIT_L(0); PG8_MMA(1, 0, At, B0); PG8_BAR; PG8_SCHED;
;             PG8_STAGE(PG8_SB(1, 1), b3 + hstep, voffB);
;             PG8_WAIT_V(6); PG8_BAR; PG8_MMA(1, 1, At, B1); PG8_BAR;
;             }
;         }
;         if constexpr (ALIGN_EPI) { if (wr == 0) PG8_BAR; }
	v_mfma_f32_16x16x32_bf16 v[64:67], v[178:181], v[210:213], v[64:67]
	s_setprio 0
	s_add_i32 s12, s35, s24
	v_lshl_add_u64 v[142:143], v[142:143], 0, s[84:85]
	s_mov_b32 m0, s12
	ds_read_b128 v[182:185], v148 offset:49152
	ds_read_b128 v[186:189], v148 offset:50176
	ds_read_b128 v[190:193], v148 offset:51200
	ds_read_b128 v[194:197], v148 offset:52224
	ds_read_b128 v[198:201], v148 offset:53248
	ds_read_b128 v[202:205], v148 offset:54272
	ds_read_b128 v[206:209], v148 offset:55296
	ds_read_b128 v[210:213], v148 offset:56320
	global_load_lds_dwordx4 v[142:143], off
	s_add_i32 m0, s12, 0x2000
	s_add_u32 s10, s10, 0x80080
	v_lshl_add_u64 v[142:143], v[214:215], 0, s[84:85]
	s_addc_u32 s11, s11, 0
	s_add_i32 s12, s54, s24
	global_load_lds_dwordx4 v[142:143], off
	v_lshl_add_u64 v[142:143], s[10:11], 0, v[128:129]
	s_mov_b32 m0, s12
	s_nop 0
	global_load_lds_dwordx4 v[142:143], off
	v_lshl_add_u64 v[142:143], s[10:11], 0, v[134:135]
	s_add_i32 m0, s12, 0x2000
	s_nop 0
	global_load_lds_dwordx4 v[142:143], off
	v_lshl_add_u64 v[142:143], v[216:217], 0, s[84:85]
	s_mov_b32 m0, s29
	s_nop 0
	global_load_lds_dwordx4 v[142:143], off
	v_lshl_add_u64 v[142:143], v[218:219], 0, s[84:85]
	s_mov_b32 m0, s90
	s_nop 0
	global_load_lds_dwordx4 v[142:143], off
	s_waitcnt vmcnt(8)
	s_waitcnt lgkmcnt(0)
	s_barrier
	s_setprio 1
	s_waitcnt lgkmcnt(0)
	v_mfma_f32_16x16x32_bf16 v[60:63], v[150:153], v[182:185], v[60:63]
	v_mfma_f32_16x16x32_bf16 v[56:59], v[158:161], v[182:185], v[56:59]
	v_mfma_f32_16x16x32_bf16 v[44:47], v[150:153], v[190:193], v[44:47]
	v_mfma_f32_16x16x32_bf16 v[40:43], v[158:161], v[190:193], v[40:43]
	v_mfma_f32_16x16x32_bf16 v[28:31], v[150:153], v[198:201], v[28:31]
	v_mfma_f32_16x16x32_bf16 v[24:27], v[158:161], v[198:201], v[24:27]
	v_mfma_f32_16x16x32_bf16 v[12:15], v[150:153], v[206:209], v[12:15]
	v_mfma_f32_16x16x32_bf16 v[8:11], v[158:161], v[206:209], v[8:11]
	v_mfma_f32_16x16x32_bf16 v[60:63], v[154:157], v[186:189], v[60:63]
	v_mfma_f32_16x16x32_bf16 v[56:59], v[162:165], v[186:189], v[56:59]
	v_mfma_f32_16x16x32_bf16 v[44:47], v[154:157], v[194:197], v[44:47]
	v_mfma_f32_16x16x32_bf16 v[40:43], v[162:165], v[194:197], v[40:43]
	v_mfma_f32_16x16x32_bf16 v[28:31], v[154:157], v[202:205], v[28:31]
	v_mfma_f32_16x16x32_bf16 v[24:27], v[162:165], v[202:205], v[24:27]
	v_mfma_f32_16x16x32_bf16 v[12:15], v[154:157], v[210:213], v[12:15]
	v_mfma_f32_16x16x32_bf16 v[8:11], v[162:165], v[210:213], v[8:11]
	s_setprio 0
	s_setprio 1
	v_mfma_f32_16x16x32_bf16 v[52:55], v[166:169], v[182:185], v[52:55]
	v_mfma_f32_16x16x32_bf16 v[48:51], v[174:177], v[182:185], v[48:51]
	v_mfma_f32_16x16x32_bf16 v[36:39], v[166:169], v[190:193], v[36:39]
	v_mfma_f32_16x16x32_bf16 v[32:35], v[174:177], v[190:193], v[32:35]
	v_mfma_f32_16x16x32_bf16 v[20:23], v[166:169], v[198:201], v[20:23]
	v_mfma_f32_16x16x32_bf16 v[16:19], v[174:177], v[198:201], v[16:19]
	v_mfma_f32_16x16x32_bf16 v[4:7], v[166:169], v[206:209], v[4:7]
	v_mfma_f32_16x16x32_bf16 v[0:3], v[174:177], v[206:209], v[0:3]
	v_mfma_f32_16x16x32_bf16 v[52:55], v[170:173], v[186:189], v[52:55]
	v_mfma_f32_16x16x32_bf16 v[48:51], v[178:181], v[186:189], v[48:51]
	v_mfma_f32_16x16x32_bf16 v[36:39], v[170:173], v[194:197], v[36:39]
	v_mfma_f32_16x16x32_bf16 v[32:35], v[178:181], v[194:197], v[32:35]
	v_mfma_f32_16x16x32_bf16 v[20:23], v[170:173], v[202:205], v[20:23]
	v_mfma_f32_16x16x32_bf16 v[16:19], v[178:181], v[202:205], v[16:19]
	v_mfma_f32_16x16x32_bf16 v[4:7], v[170:173], v[210:213], v[4:7]
	s_barrier
	v_mfma_f32_16x16x32_bf16 v[0:3], v[178:181], v[210:213], v[0:3]
	s_setprio 0
	s_add_i32 s34, s34, 2
	s_add_u32 s8, s8, 0x100
	s_addc_u32 s9, s9, 0
	s_add_u32 vcc_lo, vcc_lo, 0x100
	s_addc_u32 vcc_hi, vcc_hi, 0
	s_cmp_gt_u32 s34, 29
	s_cbranch_scc0 .LBB0_704
	s_and_b64 vcc, exec, s[4:5]
	s_cbranch_vccz .LBB0_707
	s_barrier

; #define PG8_STAGE(bufoff, gbase, voff) do { _Pragma("unroll") for (int _i = 0; _i < 2; ++_i) \
;         __builtin_amdgcn_global_load_lds((const unsigned*)((const char*)(gbase) + (voff)[_i]), (PG8_LAS unsigned*)(lds + (bufoff) + ldsw + _i * 8192), 16, 0, 0); } while (0)
; #define PG8_LDA(dst, b, h) do { _Pragma("unroll") for (int m = 0; m < 4; ++m) _Pragma("unroll") for (int k = 0; k < 2; ++k) dst[m][k] = *(const PG8_LAS bf16x8*)(lds + PG8_SA(b, h) + aoff + m * 2048 + k * 1024); } while (0)
; #define PG8_LDB(dst, b, h) do { _Pragma("unroll") for (int n = 0; n < 2; ++n) _Pragma("unroll") for (int k = 0; k < 2; ++k) dst[n][k] = *(const PG8_LAS bf16x8*)(lds + PG8_SB(b, h) + boff + n * 2048 + k * 1024); } while (0)
; #define PG8_MMA(ai, bj, At, Bt) do { __builtin_amdgcn_s_setprio(1); _Pragma("unroll") for (int m = 0; m < 4; ++m) _Pragma("unroll") for (int n = 0; n < 2; ++n) _Pragma("unroll") for (int k = 0; k < 2; ++k) \
;         acc[ai][bj][m][n] = __builtin_amdgcn_mfma_f32_16x16x32_bf16(Bt[n][k], At[m][k], acc[ai][bj][m][n], 0, 0, 0); __builtin_amdgcn_s_setprio(0); } while (0)
; #define PG8_WAIT_V(n) asm volatile("s_waitcnt vmcnt(" #n ")" ::: "memory")
; #define PG8_WAIT_L(n) asm volatile("s_waitcnt lgkmcnt(" #n ")" ::: "memory")
; template <class Epi, class Sched, bool ALIGN_EPI = false, bool SP2 = false>
; __device__ __forceinline__ void gemm_phase(PG8_LAS unsigned char* lds, const Gemm g, const Sched& S, const Epi& E) {
;     ...
;             const bool last = (t == nt - 2);
;             const char* a1 = cA + (size_t)(t + 1) * kstep;
;             const char* a2 = last ? nA : cA + (size_t)(t + 2) * kstep; const char* b2 = last ? nB : cB + (size_t)(t + 2) * kstep;
;             const char* a3 = a2 + kstep; const char* b3 = b2 + kstep;
;             if (last && has_next) S.a_ready(nxt);
;             if constexpr (SP2) {
;             PG8_LDB(B0, 0, 0); PG8_LDB(B1, 0, 1); PG8_SCHED; PG8_LDA(At, 0, 0); PG8_STAGE(PG8_SA(1, 1), a1 + hstep, voffA);
;             PG8_WAIT_V(8); PG8_WAIT_L(0); PG8_BAR; PG8_MMA(0, 0, At, B0); PG8_MMA(0, 1, At, B1); PG8_BAR; PG8_SCHED;
;             PG8_LDA(At, 0, 1); PG8_STAGE(PG8_SB(0, 0), b2, voffB); PG8_STAGE(PG8_SB(0, 1), b2 + hstep, voffB); PG8_STAGE(PG8_SA(0, 0), a2, voffA);
;             PG8_WAIT_V(8); PG8_WAIT_L(0); PG8_BAR; PG8_MMA(1, 0, At, B0); PG8_MMA(1, 1, At, B1); PG8_BAR; PG8_SCHED;
.LBB0_783:
	s_add_u32 vcc_lo, s38, 0x100
	s_addc_u32 vcc_hi, s39, 0
	s_add_i32 s54, 0, 0x10000
	s_cmpk_eq_i32 s35, 0x7c
	s_cselect_b32 s15, s1, vcc_hi
	s_cselect_b32 s14, s9, vcc_lo
	v_add_u32_e32 v140, s54, v143
	s_cselect_b32 s5, s7, s34
	s_cselect_b32 s4, s30, s31
	s_add_i32 s80, 0, 0x14000
	ds_read_b128 v[136:139], v140
	ds_read_b128 v[148:151], v140 offset:1024
	ds_read_b128 v[152:155], v140 offset:2048
	ds_read_b128 v[156:159], v140 offset:3072
	v_add_u32_e32 v140, s80, v143
	ds_read_b128 v[160:163], v140
	ds_read_b128 v[164:167], v140 offset:1024
	ds_read_b128 v[168:171], v140 offset:2048
	ds_read_b128 v[172:175], v140 offset:3072
	v_lshl_add_u64 v[140:141], s[38:39], 0, v[132:133]
	s_add_i32 m0, s91, 0xc000
	ds_read_b128 v[176:179], v146
	ds_read_b128 v[180:183], v146 offset:1024
	ds_read_b128 v[184:187], v146 offset:2048
	ds_read_b128 v[188:191], v146 offset:3072
	ds_read_b128 v[192:195], v146 offset:4096
	ds_read_b128 v[196:199], v146 offset:5120
	ds_read_b128 v[200:203], v146 offset:6144
	ds_read_b128 v[204:207], v146 offset:7168
	global_load_lds_dwordx4 v[140:141], off
	v_lshl_add_u64 v[140:141], s[38:39], 0, v[134:135]
	s_add_i32 m0, s91, 0xe000
	s_nop 0
	global_load_lds_dwordx4 v[140:141], off
	s_waitcnt vmcnt(8)
	s_waitcnt lgkmcnt(0)
	s_barrier
	s_setprio 1
	s_waitcnt lgkmcnt(0)
	v_mfma_f32_16x16x32_bf16 v[124:127], v[136:139], v[176:179], v[124:127]
	v_mfma_f32_16x16x32_bf16 v[120:123], v[152:155], v[176:179], v[120:123]
	v_mfma_f32_16x16x32_bf16 v[108:111], v[136:139], v[184:187], v[108:111]
	v_mfma_f32_16x16x32_bf16 v[104:107], v[152:155], v[184:187], v[104:107]
	v_mfma_f32_16x16x32_bf16 v[92:95], v[136:139], v[192:195], v[92:95]
	v_mfma_f32_16x16x32_bf16 v[88:91], v[152:155], v[192:195], v[88:91]
	v_mfma_f32_16x16x32_bf16 v[76:79], v[136:139], v[200:203], v[76:79]
	v_mfma_f32_16x16x32_bf16 v[72:75], v[152:155], v[200:203], v[72:75]
	v_mfma_f32_16x16x32_bf16 v[124:127], v[148:151], v[180:183], v[124:127]
	v_mfma_f32_16x16x32_bf16 v[120:123], v[156:159], v[180:183], v[120:123]
	v_mfma_f32_16x16x32_bf16 v[108:111], v[148:151], v[188:191], v[108:111]
	v_mfma_f32_16x16x32_bf16 v[104:107], v[156:159], v[188:191], v[104:107]
	v_mfma_f32_16x16x32_bf16 v[92:95], v[148:151], v[196:199], v[92:95]
	v_mfma_f32_16x16x32_bf16 v[88:91], v[156:159], v[196:199], v[88:91]
	v_mfma_f32_16x16x32_bf16 v[76:79], v[148:151], v[204:207], v[76:79]
	v_mfma_f32_16x16x32_bf16 v[72:75], v[156:159], v[204:207], v[72:75]
	s_setprio 0
	s_setprio 1
	v_mfma_f32_16x16x32_bf16 v[116:119], v[160:163], v[176:179], v[116:119]
	v_mfma_f32_16x16x32_bf16 v[112:115], v[168:171], v[176:179], v[112:115]
	v_mfma_f32_16x16x32_bf16 v[100:103], v[160:163], v[184:187], v[100:103]
	v_mfma_f32_16x16x32_bf16 v[96:99], v[168:171], v[184:187], v[96:99]
	v_mfma_f32_16x16x32_bf16 v[84:87], v[160:163], v[192:195], v[84:87]
	v_mfma_f32_16x16x32_bf16 v[80:83], v[168:171], v[192:195], v[80:83]
	v_mfma_f32_16x16x32_bf16 v[68:71], v[160:163], v[200:203], v[68:71]
	v_mfma_f32_16x16x32_bf16 v[64:67], v[168:171], v[200:203], v[64:67]
	v_mfma_f32_16x16x32_bf16 v[116:119], v[164:167], v[180:183], v[116:119]
	v_mfma_f32_16x16x32_bf16 v[112:115], v[172:175], v[180:183], v[112:115]
	v_mfma_f32_16x16x32_bf16 v[100:103], v[164:167], v[188:191], v[100:103]
	v_mfma_f32_16x16x32_bf16 v[96:99], v[172:175], v[188:191], v[96:99]
	v_mfma_f32_16x16x32_bf16 v[84:87], v[164:167], v[196:199], v[84:87]
	v_mfma_f32_16x16x32_bf16 v[80:83], v[172:175], v[196:199], v[80:83]
	v_mfma_f32_16x16x32_bf16 v[68:71], v[164:167], v[204:207], v[68:71]
	s_barrier
	v_mfma_f32_16x16x32_bf16 v[64:67], v[172:175], v[204:207], v[64:67]
	s_setprio 0
	s_add_i32 s38, s54, s23
	v_lshl_add_u64 v[140:141], s[4:5], 0, v[128:129]
	s_mov_b32 m0, s38
	ds_read_b128 v[176:179], v146 offset:16384
	ds_read_b128 v[180:183], v146 offset:17408
	ds_read_b128 v[184:187], v146 offset:18432
	ds_read_b128 v[188:191], v146 offset:19456
	ds_read_b128 v[192:195], v146 offset:20480
	ds_read_b128 v[196:199], v146 offset:21504
	ds_read_b128 v[200:203], v146 offset:22528
	ds_read_b128 v[204:207], v146 offset:23552
	global_load_lds_dwordx4 v[140:141], off
	s_add_i32 m0, s38, 0x2000
	s_add_u32 s38, s4, 0x200000
	v_lshl_add_u64 v[208:209], s[4:5], 0, v[130:131]
	s_addc_u32 s39, s5, 0
	s_add_i32 s54, s80, s23
	global_load_lds_dwordx4 v[208:209], off
	v_lshl_add_u64 v[210:211], s[38:39], 0, v[128:129]
	s_mov_b32 m0, s54
	v_lshl_add_u64 v[212:213], s[14:15], 0, v[130:131]
	global_load_lds_dwordx4 v[210:211], off
	v_lshl_add_u64 v[210:211], s[38:39], 0, v[130:131]
	s_add_i32 m0, s54, 0x2000
	s_nop 0
	global_load_lds_dwordx4 v[210:211], off
	v_lshl_add_u64 v[210:211], s[14:15], 0, v[128:129]
	s_mov_b32 m0, s91
	s_nop 0
	global_load_lds_dwordx4 v[210:211], off
	s_mov_b32 m0, s24
	s_nop 0
	global_load_lds_dwordx4 v[212:213], off
	s_waitcnt vmcnt(8)
	s_waitcnt lgkmcnt(0)
	s_barrier
; #define PG8_STAGE(bufoff, gbase, voff) do { _Pragma("unroll") for (int _i = 0; _i < 2; ++_i) \
;         __builtin_amdgcn_global_load_lds((const unsigned*)((const char*)(gbase) + (voff)[_i]), (PG8_LAS unsigned*)(lds + (bufoff) + ldsw + _i * 8192), 16, 0, 0); } while (0)
; #define PG8_LDA(dst, b, h) do { _Pragma("unroll") for (int m = 0; m < 4; ++m) _Pragma("unroll") for (int k = 0; k < 2; ++k) dst[m][k] = *(const PG8_LAS bf16x8*)(lds + PG8_SA(b, h) + aoff + m * 2048 + k * 1024); } while (0)
; #define PG8_LDB(dst, b, h) do { _Pragma("unroll") for (int n = 0; n < 2; ++n) _Pragma("unroll") for (int k = 0; k < 2; ++k) dst[n][k] = *(const PG8_LAS bf16x8*)(lds + PG8_SB(b, h) + boff + n * 2048 + k * 1024); } while (0)
; #define PG8_MMA(ai, bj, At, Bt) do { __builtin_amdgcn_s_setprio(1); _Pragma("unroll") for (int m = 0; m < 4; ++m) _Pragma("unroll") for (int n = 0; n < 2; ++n) _Pragma("unroll") for (int k = 0; k < 2; ++k) \
;         acc[ai][bj][m][n] = __builtin_amdgcn_mfma_f32_16x16x32_bf16(Bt[n][k], At[m][k], acc[ai][bj][m][n], 0, 0, 0); __builtin_amdgcn_s_setprio(0); } while (0)
; #define PG8_WAIT_V(n) asm volatile("s_waitcnt vmcnt(" #n ")" ::: "memory")
; #define PG8_WAIT_L(n) asm volatile("s_waitcnt lgkmcnt(" #n ")" ::: "memory")
; #define PG8_BAR __builtin_amdgcn_s_barrier()
; #define PG8_SCHED __builtin_amdgcn_sched_barrier(0)
; template <class Epi, class Sched, bool ALIGN_EPI = false, bool SP2 = false>
; __device__ __forceinline__ void gemm_phase(PG8_LAS unsigned char* lds, const Gemm g, const Sched& S, const Epi& E) {
;     ...
;             PG8_WAIT_V(8); PG8_WAIT_L(0); PG8_BAR; PG8_MMA(0, 0, At, B0); PG8_MMA(0, 1, At, B1); PG8_BAR; PG8_SCHED;
;             PG8_LDA(At, 0, 1); PG8_STAGE(PG8_SB(0, 0), b2, voffB); PG8_STAGE(PG8_SB(0, 1), b2 + hstep, voffB); PG8_STAGE(PG8_SA(0, 0), a2, voffA);
;             PG8_WAIT_V(8); PG8_WAIT_L(0); PG8_BAR; PG8_MMA(1, 0, At, B0); PG8_MMA(1, 1, At, B1); PG8_BAR; PG8_SCHED;
;             PG8_LDB(B0, 1, 0); PG8_LDB(B1, 1, 1); PG8_SCHED; PG8_LDA(At, 1, 0); PG8_STAGE(PG8_SA(0, 1), a2 + hstep, voffA);
;             PG8_WAIT_V(8); PG8_WAIT_L(0); PG8_BAR; PG8_MMA(0, 0, At, B0); PG8_MMA(0, 1, At, B1); PG8_BAR; PG8_SCHED;
	s_setprio 1
	s_waitcnt lgkmcnt(0)
	v_mfma_f32_16x16x32_bf16 v[60:63], v[136:139], v[176:179], v[60:63]
	v_mfma_f32_16x16x32_bf16 v[56:59], v[152:155], v[176:179], v[56:59]
	v_mfma_f32_16x16x32_bf16 v[44:47], v[136:139], v[184:187], v[44:47]
	v_mfma_f32_16x16x32_bf16 v[40:43], v[152:155], v[184:187], v[40:43]
	v_mfma_f32_16x16x32_bf16 v[28:31], v[136:139], v[192:195], v[28:31]
	v_mfma_f32_16x16x32_bf16 v[24:27], v[152:155], v[192:195], v[24:27]
	v_mfma_f32_16x16x32_bf16 v[12:15], v[136:139], v[200:203], v[12:15]
	v_mfma_f32_16x16x32_bf16 v[8:11], v[152:155], v[200:203], v[8:11]
	v_mfma_f32_16x16x32_bf16 v[60:63], v[148:151], v[180:183], v[60:63]
	v_mfma_f32_16x16x32_bf16 v[56:59], v[156:159], v[180:183], v[56:59]
	v_mfma_f32_16x16x32_bf16 v[44:47], v[148:151], v[188:191], v[44:47]
	v_mfma_f32_16x16x32_bf16 v[40:43], v[156:159], v[188:191], v[40:43]
	v_mfma_f32_16x16x32_bf16 v[28:31], v[148:151], v[196:199], v[28:31]
	v_mfma_f32_16x16x32_bf16 v[24:27], v[156:159], v[196:199], v[24:27]
	v_mfma_f32_16x16x32_bf16 v[12:15], v[148:151], v[204:207], v[12:15]
	v_mfma_f32_16x16x32_bf16 v[8:11], v[156:159], v[204:207], v[8:11]
	s_setprio 0
	s_setprio 1
	v_mfma_f32_16x16x32_bf16 v[52:55], v[160:163], v[176:179], v[52:55]
	v_mfma_f32_16x16x32_bf16 v[48:51], v[168:171], v[176:179], v[48:51]
	v_mfma_f32_16x16x32_bf16 v[36:39], v[160:163], v[184:187], v[36:39]
	v_mfma_f32_16x16x32_bf16 v[32:35], v[168:171], v[184:187], v[32:35]
	v_mfma_f32_16x16x32_bf16 v[20:23], v[160:163], v[192:195], v[20:23]
	v_mfma_f32_16x16x32_bf16 v[16:19], v[168:171], v[192:195], v[16:19]
	v_mfma_f32_16x16x32_bf16 v[4:7], v[160:163], v[200:203], v[4:7]
	v_mfma_f32_16x16x32_bf16 v[0:3], v[168:171], v[200:203], v[0:3]
	v_mfma_f32_16x16x32_bf16 v[52:55], v[164:167], v[180:183], v[52:55]
	v_mfma_f32_16x16x32_bf16 v[48:51], v[172:175], v[180:183], v[48:51]
	v_mfma_f32_16x16x32_bf16 v[36:39], v[164:167], v[188:191], v[36:39]
	v_mfma_f32_16x16x32_bf16 v[32:35], v[172:175], v[188:191], v[32:35]
	v_mfma_f32_16x16x32_bf16 v[20:23], v[164:167], v[196:199], v[20:23]
	v_mfma_f32_16x16x32_bf16 v[16:19], v[172:175], v[196:199], v[16:19]
	v_mfma_f32_16x16x32_bf16 v[4:7], v[164:167], v[204:207], v[4:7]
	s_barrier
	v_mfma_f32_16x16x32_bf16 v[0:3], v[172:175], v[204:207], v[0:3]
	s_setprio 0
	s_add_i32 s38, 0, 0x18000
	v_add_u32_e32 v147, s38, v143
	s_add_i32 s39, 0, 0x1c000
	ds_read_b128 v[136:139], v147
	ds_read_b128 v[148:151], v147 offset:1024
	ds_read_b128 v[152:155], v147 offset:2048
	ds_read_b128 v[156:159], v147 offset:3072
	v_add_u32_e32 v147, s39, v143
	ds_read_b128 v[160:163], v147
	ds_read_b128 v[164:167], v147 offset:1024
	ds_read_b128 v[168:171], v147 offset:2048
	ds_read_b128 v[172:175], v147 offset:3072
	s_add_u32 s14, s14, 0x200000
	s_addc_u32 s15, s15, 0
	s_mov_b32 m0, s25
	v_lshl_add_u64 v[214:215], s[14:15], 0, v[128:129]
	ds_read_b128 v[176:179], v146 offset:32768
	ds_read_b128 v[180:183], v146 offset:33792
	ds_read_b128 v[184:187], v146 offset:34816
	ds_read_b128 v[188:191], v146 offset:35840
	ds_read_b128 v[192:195], v146 offset:36864
	ds_read_b128 v[196:199], v146 offset:37888
	ds_read_b128 v[200:203], v146 offset:38912
	ds_read_b128 v[204:207], v146 offset:39936
	global_load_lds_dwordx4 v[214:215], off
	v_lshl_add_u64 v[214:215], s[14:15], 0, v[130:131]
	s_mov_b32 m0, s26
	s_nop 0
	global_load_lds_dwordx4 v[214:215], off
	s_waitcnt vmcnt(8)
	s_waitcnt lgkmcnt(0)
	s_barrier
	s_setprio 1
	s_waitcnt lgkmcnt(0)
	v_mfma_f32_16x16x32_bf16 v[124:127], v[136:139], v[176:179], v[124:127]
	v_mfma_f32_16x16x32_bf16 v[120:123], v[152:155], v[176:179], v[120:123]
	v_mfma_f32_16x16x32_bf16 v[108:111], v[136:139], v[184:187], v[108:111]
	v_mfma_f32_16x16x32_bf16 v[104:107], v[152:155], v[184:187], v[104:107]
	v_mfma_f32_16x16x32_bf16 v[92:95], v[136:139], v[192:195], v[92:95]
	v_mfma_f32_16x16x32_bf16 v[88:91], v[152:155], v[192:195], v[88:91]
	v_mfma_f32_16x16x32_bf16 v[76:79], v[136:139], v[200:203], v[76:79]
	v_mfma_f32_16x16x32_bf16 v[72:75], v[152:155], v[200:203], v[72:75]
	v_mfma_f32_16x16x32_bf16 v[124:127], v[148:151], v[180:183], v[124:127]
	v_mfma_f32_16x16x32_bf16 v[120:123], v[156:159], v[180:183], v[120:123]
	v_mfma_f32_16x16x32_bf16 v[108:111], v[148:151], v[188:191], v[108:111]
	v_mfma_f32_16x16x32_bf16 v[104:107], v[156:159], v[188:191], v[104:107]
	v_mfma_f32_16x16x32_bf16 v[92:95], v[148:151], v[196:199], v[92:95]
	v_mfma_f32_16x16x32_bf16 v[88:91], v[156:159], v[196:199], v[88:91]
	v_mfma_f32_16x16x32_bf16 v[76:79], v[148:151], v[204:207], v[76:79]
	v_mfma_f32_16x16x32_bf16 v[72:75], v[156:159], v[204:207], v[72:75]
	s_setprio 0
	s_setprio 1
	v_mfma_f32_16x16x32_bf16 v[116:119], v[160:163], v[176:179], v[116:119]
	v_mfma_f32_16x16x32_bf16 v[112:115], v[168:171], v[176:179], v[112:115]
	v_mfma_f32_16x16x32_bf16 v[100:103], v[160:163], v[184:187], v[100:103]
	v_mfma_f32_16x16x32_bf16 v[96:99], v[168:171], v[184:187], v[96:99]
	v_mfma_f32_16x16x32_bf16 v[84:87], v[160:163], v[192:195], v[84:87]
	v_mfma_f32_16x16x32_bf16 v[80:83], v[168:171], v[192:195], v[80:83]
	v_mfma_f32_16x16x32_bf16 v[68:71], v[160:163], v[200:203], v[68:71]
	v_mfma_f32_16x16x32_bf16 v[64:67], v[168:171], v[200:203], v[64:67]
	v_mfma_f32_16x16x32_bf16 v[116:119], v[164:167], v[180:183], v[116:119]
	v_mfma_f32_16x16x32_bf16 v[112:115], v[172:175], v[180:183], v[112:115]
	v_mfma_f32_16x16x32_bf16 v[100:103], v[164:167], v[188:191], v[100:103]
	v_mfma_f32_16x16x32_bf16 v[96:99], v[172:175], v[188:191], v[96:99]
	v_mfma_f32_16x16x32_bf16 v[84:87], v[164:167], v[196:199], v[84:87]
	v_mfma_f32_16x16x32_bf16 v[80:83], v[172:175], v[196:199], v[80:83]
	v_mfma_f32_16x16x32_bf16 v[68:71], v[164:167], v[204:207], v[68:71]
	s_barrier
; #define PG8_STAGE(bufoff, gbase, voff) do { _Pragma("unroll") for (int _i = 0; _i < 2; ++_i) \
;         __builtin_amdgcn_global_load_lds((const unsigned*)((const char*)(gbase) + (voff)[_i]), (PG8_LAS unsigned*)(lds + (bufoff) + ldsw + _i * 8192), 16, 0, 0); } while (0)
; #define PG8_WAIT_V(n) asm volatile("s_waitcnt vmcnt(" #n ")" ::: "memory")
; #define PG8_WAIT_L(n) asm volatile("s_waitcnt lgkmcnt(" #n ")" ::: "memory")
; template <class Epi, class Sched, bool ALIGN_EPI = false, bool SP2 = false>
; __device__ __forceinline__ void gemm_phase(PG8_LAS unsigned char* lds, const Gemm g, const Sched& S, const Epi& E) {
;     ...
;             PG8_WAIT_V(8); PG8_WAIT_L(0); PG8_BAR; PG8_MMA(0, 0, At, B0); PG8_MMA(0, 1, At, B1); PG8_BAR; PG8_SCHED;
;             PG8_LDA(At, 1, 1); PG8_STAGE(PG8_SB(1, 0), b3, voffB); PG8_STAGE(PG8_SB(1, 1), b3 + hstep, voffB); PG8_STAGE(PG8_SA(1, 0), a3, voffA);
;             PG8_WAIT_V(8); PG8_WAIT_L(0); PG8_BAR; PG8_MMA(1, 0, At, B0); PG8_MMA(1, 1, At, B1); PG8_BAR; PG8_SCHED;
;             } else {
;             PG8_LDB(B0, 0, 0); PG8_SCHED; PG8_LDA(At, 0, 0); PG8_STAGE(PG8_SA(1, 1), a1 + hstep, voffA);
;             PG8_WAIT_L(8); PG8_BAR; PG8_WAIT_L(0); PG8_MMA(0, 0, At, B0); PG8_BAR; PG8_SCHED;
;             PG8_LDB(B1, 0, 1); PG8_STAGE(PG8_SB(0, 0), b2, voffB);
;             PG8_BAR; PG8_WAIT_L(0); PG8_MMA(0, 1, At, B1); PG8_BAR;
;             PG8_LDA(At, 0, 1); PG8_STAGE(PG8_SA(0, 0), a2, voffA);
;             PG8_BAR; PG8_WAIT_L(0); PG8_MMA(1, 0, At, B0); PG8_BAR; PG8_SCHED;
;             PG8_STAGE(PG8_SB(0, 1), b2 + hstep, voffB);
;             PG8_WAIT_V(6); PG8_BAR; PG8_MMA(1, 1, At, B1); PG8_BAR;
;             PG8_LDB(B0, 1, 0); PG8_SCHED; PG8_LDA(At, 1, 0); PG8_STAGE(PG8_SA(0, 1), a2 + hstep, voffA);
;             PG8_WAIT_L(8); PG8_BAR; PG8_WAIT_L(0); PG8_MMA(0, 0, At, B0); PG8_BAR; PG8_SCHED;
;             PG8_LDB(B1, 1, 1); PG8_STAGE(PG8_SB(1, 0), b3, voffB);
;             PG8_BAR; PG8_WAIT_L(0); PG8_MMA(0, 1, At, B1); PG8_BAR;
;             PG8_LDA(At, 1, 1); PG8_STAGE(PG8_SA(1, 0), a3, voffA);
;             PG8_BAR; PG8_WAIT_L(0); PG8_MMA(1, 0, At, B0); PG8_BAR; PG8_SCHED;
;             PG8_STAGE(PG8_SB(1, 1), b3 + hstep, voffB);
;             PG8_WAIT_V(6); PG8_BAR; PG8_MMA(1, 1, At, B1); PG8_BAR;
;             }
;         }
;         if constexpr (ALIGN_EPI) { if (wr == 0) PG8_BAR; }
	v_mfma_f32_16x16x32_bf16 v[64:67], v[172:175], v[204:207], v[64:67]
	s_setprio 0
	s_add_i32 s14, s38, s23
	v_lshl_add_u64 v[140:141], v[140:141], 0, s[84:85]
	s_mov_b32 m0, s14
	ds_read_b128 v[176:179], v146 offset:49152
	ds_read_b128 v[180:183], v146 offset:50176
	ds_read_b128 v[184:187], v146 offset:51200
	ds_read_b128 v[188:191], v146 offset:52224
	ds_read_b128 v[192:195], v146 offset:53248
	ds_read_b128 v[196:199], v146 offset:54272
	ds_read_b128 v[200:203], v146 offset:55296
	ds_read_b128 v[204:207], v146 offset:56320
	global_load_lds_dwordx4 v[140:141], off
	s_add_i32 m0, s14, 0x2000
	s_add_u32 s4, s4, 0x200080
	v_lshl_add_u64 v[140:141], v[208:209], 0, s[84:85]
	s_addc_u32 s5, s5, 0
	s_add_i32 s14, s39, s23
	global_load_lds_dwordx4 v[140:141], off
	v_lshl_add_u64 v[140:141], s[4:5], 0, v[128:129]
	s_mov_b32 m0, s14
	s_nop 0
	global_load_lds_dwordx4 v[140:141], off
	v_lshl_add_u64 v[140:141], s[4:5], 0, v[130:131]
	s_add_i32 m0, s14, 0x2000
	s_nop 0
	global_load_lds_dwordx4 v[140:141], off
	v_lshl_add_u64 v[140:141], v[210:211], 0, s[84:85]
	s_mov_b32 m0, s20
	s_nop 0
	global_load_lds_dwordx4 v[140:141], off
	v_lshl_add_u64 v[140:141], v[212:213], 0, s[84:85]
	s_mov_b32 m0, s27
	s_nop 0
	global_load_lds_dwordx4 v[140:141], off
	s_waitcnt vmcnt(8)
	s_waitcnt lgkmcnt(0)
	s_barrier
	s_setprio 1
	s_waitcnt lgkmcnt(0)
	v_mfma_f32_16x16x32_bf16 v[60:63], v[136:139], v[176:179], v[60:63]
	v_mfma_f32_16x16x32_bf16 v[56:59], v[152:155], v[176:179], v[56:59]
	v_mfma_f32_16x16x32_bf16 v[44:47], v[136:139], v[184:187], v[44:47]
	v_mfma_f32_16x16x32_bf16 v[40:43], v[152:155], v[184:187], v[40:43]
	v_mfma_f32_16x16x32_bf16 v[28:31], v[136:139], v[192:195], v[28:31]
	v_mfma_f32_16x16x32_bf16 v[24:27], v[152:155], v[192:195], v[24:27]
	v_mfma_f32_16x16x32_bf16 v[12:15], v[136:139], v[200:203], v[12:15]
	v_mfma_f32_16x16x32_bf16 v[8:11], v[152:155], v[200:203], v[8:11]
	v_mfma_f32_16x16x32_bf16 v[60:63], v[148:151], v[180:183], v[60:63]
	v_mfma_f32_16x16x32_bf16 v[56:59], v[156:159], v[180:183], v[56:59]
	v_mfma_f32_16x16x32_bf16 v[44:47], v[148:151], v[188:191], v[44:47]
	v_mfma_f32_16x16x32_bf16 v[40:43], v[156:159], v[188:191], v[40:43]
	v_mfma_f32_16x16x32_bf16 v[28:31], v[148:151], v[196:199], v[28:31]
	v_mfma_f32_16x16x32_bf16 v[24:27], v[156:159], v[196:199], v[24:27]
	v_mfma_f32_16x16x32_bf16 v[12:15], v[148:151], v[204:207], v[12:15]
	v_mfma_f32_16x16x32_bf16 v[8:11], v[156:159], v[204:207], v[8:11]
	s_setprio 0
	s_setprio 1
	v_mfma_f32_16x16x32_bf16 v[52:55], v[160:163], v[176:179], v[52:55]
	v_mfma_f32_16x16x32_bf16 v[48:51], v[168:171], v[176:179], v[48:51]
	v_mfma_f32_16x16x32_bf16 v[36:39], v[160:163], v[184:187], v[36:39]
	v_mfma_f32_16x16x32_bf16 v[32:35], v[168:171], v[184:187], v[32:35]
	v_mfma_f32_16x16x32_bf16 v[20:23], v[160:163], v[192:195], v[20:23]
	v_mfma_f32_16x16x32_bf16 v[16:19], v[168:171], v[192:195], v[16:19]
	v_mfma_f32_16x16x32_bf16 v[4:7], v[160:163], v[200:203], v[4:7]
	v_mfma_f32_16x16x32_bf16 v[0:3], v[168:171], v[200:203], v[0:3]
	v_mfma_f32_16x16x32_bf16 v[52:55], v[164:167], v[180:183], v[52:55]
	v_mfma_f32_16x16x32_bf16 v[48:51], v[172:175], v[180:183], v[48:51]
	v_mfma_f32_16x16x32_bf16 v[36:39], v[164:167], v[188:191], v[36:39]
	v_mfma_f32_16x16x32_bf16 v[32:35], v[172:175], v[188:191], v[32:35]
	v_mfma_f32_16x16x32_bf16 v[20:23], v[164:167], v[196:199], v[20:23]
	v_mfma_f32_16x16x32_bf16 v[16:19], v[172:175], v[196:199], v[16:19]
	v_mfma_f32_16x16x32_bf16 v[4:7], v[164:167], v[204:207], v[4:7]
	s_barrier
	v_mfma_f32_16x16x32_bf16 v[0:3], v[172:175], v[204:207], v[0:3]
	s_setprio 0
	s_add_i32 s35, s35, 2
	s_add_u32 s31, s31, 0x100
	s_addc_u32 s34, s34, 0
	s_cmpk_gt_u32 s35, 0x7d
	s_mov_b64 s[38:39], vcc
	s_cbranch_scc0 .LBB0_783
	s_and_b64 vcc, exec, s[96:97]
	s_cbranch_vccz .LBB0_786
	s_barrier
